# K1+C+noprio plus merged the vmcnt/lgkmcnt waits before each K-loop barrier and dropped the redundant lgkmcnt(0) after it
# speedup vs baseline: 1.0023x; 1.0023x over previous
; #define PG8_STAGE(bufoff, gbase, voff) do { _Pragma("unroll") for (int _i = 0; _i < 2; ++_i) \
;         __builtin_amdgcn_global_load_lds((const unsigned*)((const char*)(gbase) + (voff)[_i]), (PG8_LAS unsigned*)(lds + (bufoff) + ldsw + _i * 8192), 16, 0, 0); } while (0)
; #define PG8_LDA(dst, b, h) do { _Pragma("unroll") for (int m = 0; m < 4; ++m) _Pragma("unroll") for (int k = 0; k < 2; ++k) dst[m][k] = *(const PG8_LAS bf16x8*)(lds + PG8_SA(b, h) + aoff + m * 2048 + k * 1024); } while (0)
; template <class Epi, class Sched, bool ALIGN_EPI = false, bool SP2 = false>
; __device__ __forceinline__ void gemm_phase(PG8_LAS unsigned char* lds, const Gemm g, const Sched& S, const Epi& E) {
;     ...
;         const bool has_next = S.next(ui + 1, nxt);
;         const char* nA = has_next ? (const char*)g.A + (size_t)nxt.pm * tstep : cA; const char* nB = has_next ? (const char*)g.Bt + (size_t)nxt.pn * tstep : cB;
;         for (int t = 0; t < nt; t += 2) {
;             const bool last = (t == nt - 2);
;             const char* a1 = cA + (size_t)(t + 1) * kstep;
;             const char* a2 = last ? nA : cA + (size_t)(t + 2) * kstep; const char* b2 = last ? nB : cB + (size_t)(t + 2) * kstep;
;             const char* a3 = a2 + kstep; const char* b3 = b2 + kstep;
;             if (last && has_next) S.a_ready(nxt);
;             if constexpr (SP2) {
;             PG8_LDB(B0, 0, 0); PG8_LDB(B1, 0, 1); PG8_SCHED; PG8_LDA(At, 0, 0); PG8_STAGE(PG8_SA(1, 1), a1 + hstep, voffA);
;             PG8_WAIT_V(8); PG8_WAIT_L(0); PG8_BAR; PG8_MMA(0, 0, At, B0); PG8_MMA(0, 1, At, B1); PG8_BAR; PG8_SCHED;
;             PG8_LDA(At, 0, 1); PG8_STAGE(PG8_SB(0, 0), b2, voffB); PG8_STAGE(PG8_SB(0, 1), b2 + hstep, voffB); PG8_STAGE(PG8_SA(0, 0), a2, voffA);
;             PG8_WAIT_V(8); PG8_WAIT_L(0); PG8_BAR; PG8_MMA(1, 0, At, B0); PG8_MMA(1, 1, At, B1); PG8_BAR; PG8_SCHED;
;             PG8_LDB(B0, 1, 0); PG8_LDB(B1, 1, 1); PG8_SCHED; PG8_LDA(At, 1, 0); PG8_STAGE(PG8_SA(0, 1), a2 + hstep, voffA);
;             PG8_WAIT_V(8); PG8_WAIT_L(0); PG8_BAR; PG8_MMA(0, 0, At, B0); PG8_MMA(0, 1, At, B1); PG8_BAR; PG8_SCHED;
;             PG8_LDA(At, 1, 1); PG8_STAGE(PG8_SB(1, 0), b3, voffB); PG8_STAGE(PG8_SB(1, 1), b3 + hstep, voffB); PG8_STAGE(PG8_SA(1, 0), a3, voffA);
;             PG8_WAIT_V(8); PG8_WAIT_L(0); PG8_BAR; PG8_MMA(1, 0, At, B0); PG8_MMA(1, 1, At, B1); PG8_BAR; PG8_SCHED;
.LBB0_905:
	s_ashr_i32 s13, s12, 31
	s_lshl_b64 s[14:15], s[12:13], 17
	s_add_u32 s14, s22, s14
	s_addc_u32 s15, s23, s15
	s_and_b64 s[16:17], s[2:3], exec
	s_cselect_b32 s71, s15, s19
	s_cselect_b32 s70, s14, s18
	s_ashr_i32 s11, s10, 31
	s_lshl_b64 s[16:17], s[10:11], 17
	s_add_u32 s16, s27, s16
	s_addc_u32 s17, s28, s17
	s_and_b64 s[64:65], s[2:3], exec
	s_cselect_b32 s69, s17, s67
	s_cselect_b32 s68, s16, s66
	s_add_u32 s74, s18, 0x10000
	s_addc_u32 s75, s19, 0
	s_add_u32 s76, s66, 0x10000
	s_addc_u32 s77, s67, 0
	s_add_u32 s72, s18, 0x18000
	s_addc_u32 s73, s19, 0
	s_add_i32 s59, 0, 0x10000
	s_add_i32 s13, 0, 0x14000
	v_add_u32_e32 v202, s59, v206
	v_add_u32_e32 v203, s13, v206
	ds_read_b128 v[128:131], v202
	ds_read_b128 v[132:135], v202 offset:1024
	ds_read_b128 v[136:139], v202 offset:2048
	ds_read_b128 v[140:143], v202 offset:3072
	ds_read_b128 v[144:147], v203
	ds_read_b128 v[148:151], v203 offset:1024
	ds_read_b128 v[152:155], v203 offset:2048
	ds_read_b128 v[156:159], v203 offset:3072
	s_add_u32 s80, s18, 0xc000
	s_addc_u32 s81, s19, 0
	s_add_i32 s64, s33, 0xc000
	s_mov_b32 m0, s64
	s_add_i32 s5, s33, 0xe000
	ds_read_b128 v[168:171], v207
	ds_read_b128 v[172:175], v207 offset:1024
	ds_read_b128 v[176:179], v207 offset:2048
	ds_read_b128 v[180:183], v207 offset:3072
	ds_read_b128 v[184:187], v207 offset:4096
	ds_read_b128 v[188:191], v207 offset:5120
	ds_read_b128 v[192:195], v207 offset:6144
	ds_read_b128 v[196:199], v207 offset:7168
	global_load_lds_dwordx4 v160, s[80:81]
	s_mov_b32 m0, s5
	s_nop 0
	global_load_lds_dwordx4 v164, s[80:81]
	s_waitcnt vmcnt(8) lgkmcnt(0)
	s_barrier
	v_mfma_f32_16x16x32_bf16 v[124:127], v[128:131], v[168:171], v[124:127]
	v_mfma_f32_16x16x32_bf16 v[120:123], v[136:139], v[168:171], v[120:123]
	v_mfma_f32_16x16x32_bf16 v[116:119], v[128:131], v[176:179], v[116:119]
	v_mfma_f32_16x16x32_bf16 v[112:115], v[136:139], v[176:179], v[112:115]
	v_mfma_f32_16x16x32_bf16 v[108:111], v[128:131], v[184:187], v[108:111]
	v_mfma_f32_16x16x32_bf16 v[104:107], v[136:139], v[184:187], v[104:107]
	v_mfma_f32_16x16x32_bf16 v[100:103], v[128:131], v[192:195], v[100:103]
	v_mfma_f32_16x16x32_bf16 v[96:99], v[136:139], v[192:195], v[96:99]
	v_mfma_f32_16x16x32_bf16 v[124:127], v[132:135], v[172:175], v[124:127]
	v_mfma_f32_16x16x32_bf16 v[120:123], v[140:143], v[172:175], v[120:123]
	v_mfma_f32_16x16x32_bf16 v[116:119], v[132:135], v[180:183], v[116:119]
	v_mfma_f32_16x16x32_bf16 v[112:115], v[140:143], v[180:183], v[112:115]
	v_mfma_f32_16x16x32_bf16 v[108:111], v[132:135], v[188:191], v[108:111]
	v_mfma_f32_16x16x32_bf16 v[104:107], v[140:143], v[188:191], v[104:107]
	v_mfma_f32_16x16x32_bf16 v[100:103], v[132:135], v[196:199], v[100:103]
	v_mfma_f32_16x16x32_bf16 v[96:99], v[140:143], v[196:199], v[96:99]
	v_mfma_f32_16x16x32_bf16 v[92:95], v[144:147], v[168:171], v[92:95]
	v_mfma_f32_16x16x32_bf16 v[88:91], v[152:155], v[168:171], v[88:91]
	v_mfma_f32_16x16x32_bf16 v[84:87], v[144:147], v[176:179], v[84:87]
	v_mfma_f32_16x16x32_bf16 v[80:83], v[152:155], v[176:179], v[80:83]
	v_mfma_f32_16x16x32_bf16 v[76:79], v[144:147], v[184:187], v[76:79]
	v_mfma_f32_16x16x32_bf16 v[72:75], v[152:155], v[184:187], v[72:75]
	v_mfma_f32_16x16x32_bf16 v[68:71], v[144:147], v[192:195], v[68:71]
	v_mfma_f32_16x16x32_bf16 v[64:67], v[152:155], v[192:195], v[64:67]
	v_mfma_f32_16x16x32_bf16 v[92:95], v[148:151], v[172:175], v[92:95]
	v_mfma_f32_16x16x32_bf16 v[88:91], v[156:159], v[172:175], v[88:91]
	v_mfma_f32_16x16x32_bf16 v[84:87], v[148:151], v[180:183], v[84:87]
	v_mfma_f32_16x16x32_bf16 v[80:83], v[156:159], v[180:183], v[80:83]
	v_mfma_f32_16x16x32_bf16 v[76:79], v[148:151], v[188:191], v[76:79]
	v_mfma_f32_16x16x32_bf16 v[72:75], v[156:159], v[188:191], v[72:75]
	v_mfma_f32_16x16x32_bf16 v[68:71], v[148:151], v[196:199], v[68:71]
	v_mfma_f32_16x16x32_bf16 v[64:67], v[156:159], v[196:199], v[64:67]
	s_barrier
	s_add_i32 s59, s59, s30
	s_mov_b32 m0, s59
	s_add_i32 s11, s59, 0x2000
	ds_read_b128 v[168:171], v207 offset:16384
	ds_read_b128 v[172:175], v207 offset:17408
	ds_read_b128 v[176:179], v207 offset:18432
	ds_read_b128 v[180:183], v207 offset:19456
	ds_read_b128 v[184:187], v207 offset:20480
	ds_read_b128 v[188:191], v207 offset:21504
	ds_read_b128 v[192:195], v207 offset:22528
	ds_read_b128 v[196:199], v207 offset:23552
	global_load_lds_dwordx4 v162, s[76:77]
	v_lshl_add_u64 v[200:201], s[76:77], 0, v[166:167]
	s_add_u32 s76, s66, 0x14000
	s_mov_b32 m0, s11
	s_addc_u32 s77, s67, 0
	s_add_i32 s13, s13, s30
	global_load_lds_dwordx4 v[200:201], off
	s_mov_b32 m0, s13
	s_add_i32 s21, s13, 0x2000
	global_load_lds_dwordx4 v162, s[76:77]
	s_mov_b32 m0, s21
	s_nop 0
	global_load_lds_dwordx4 v166, s[76:77]
	s_mov_b32 m0, s33
	s_nop 0
	global_load_lds_dwordx4 v160, s[74:75]
	s_mov_b32 m0, s37
	s_nop 0
	global_load_lds_dwordx4 v164, s[74:75]
	s_waitcnt vmcnt(8) lgkmcnt(0)
	s_barrier
; #define PG8_STAGE(bufoff, gbase, voff) do { _Pragma("unroll") for (int _i = 0; _i < 2; ++_i) \
;         __builtin_amdgcn_global_load_lds((const unsigned*)((const char*)(gbase) + (voff)[_i]), (PG8_LAS unsigned*)(lds + (bufoff) + ldsw + _i * 8192), 16, 0, 0); } while (0)
; #define PG8_LDA(dst, b, h) do { _Pragma("unroll") for (int m = 0; m < 4; ++m) _Pragma("unroll") for (int k = 0; k < 2; ++k) dst[m][k] = *(const PG8_LAS bf16x8*)(lds + PG8_SA(b, h) + aoff + m * 2048 + k * 1024); } while (0)
; #define PG8_LDB(dst, b, h) do { _Pragma("unroll") for (int n = 0; n < 2; ++n) _Pragma("unroll") for (int k = 0; k < 2; ++k) dst[n][k] = *(const PG8_LAS bf16x8*)(lds + PG8_SB(b, h) + boff + n * 2048 + k * 1024); } while (0)
; #define PG8_MMA(ai, bj, At, Bt) do { __builtin_amdgcn_s_setprio(1); _Pragma("unroll") for (int m = 0; m < 4; ++m) _Pragma("unroll") for (int n = 0; n < 2; ++n) _Pragma("unroll") for (int k = 0; k < 2; ++k) \
;         acc[ai][bj][m][n] = __builtin_amdgcn_mfma_f32_16x16x32_bf16(Bt[n][k], At[m][k], acc[ai][bj][m][n], 0, 0, 0); __builtin_amdgcn_s_setprio(0); } while (0)
; #define PG8_WAIT_V(n) asm volatile("s_waitcnt vmcnt(" #n ")" ::: "memory")
; template <class Epi, class Sched, bool ALIGN_EPI = false, bool SP2 = false>
; __device__ __forceinline__ void gemm_phase(PG8_LAS unsigned char* lds, const Gemm g, const Sched& S, const Epi& E) {
;     ...
;             PG8_LDB(B0, 0, 0); PG8_LDB(B1, 0, 1); PG8_SCHED; PG8_LDA(At, 0, 0); PG8_STAGE(PG8_SA(1, 1), a1 + hstep, voffA);
;             PG8_WAIT_V(8); PG8_WAIT_L(0); PG8_BAR; PG8_MMA(0, 0, At, B0); PG8_MMA(0, 1, At, B1); PG8_BAR; PG8_SCHED;
;             PG8_LDA(At, 0, 1); PG8_STAGE(PG8_SB(0, 0), b2, voffB); PG8_STAGE(PG8_SB(0, 1), b2 + hstep, voffB); PG8_STAGE(PG8_SA(0, 0), a2, voffA);
;             PG8_WAIT_V(8); PG8_WAIT_L(0); PG8_BAR; PG8_MMA(1, 0, At, B0); PG8_MMA(1, 1, At, B1); PG8_BAR; PG8_SCHED;
;             PG8_LDB(B0, 1, 0); PG8_LDB(B1, 1, 1); PG8_SCHED; PG8_LDA(At, 1, 0); PG8_STAGE(PG8_SA(0, 1), a2 + hstep, voffA);
;             PG8_WAIT_V(8); PG8_WAIT_L(0); PG8_BAR; PG8_MMA(0, 0, At, B0); PG8_MMA(0, 1, At, B1); PG8_BAR; PG8_SCHED;
;             PG8_LDA(At, 1, 1); PG8_STAGE(PG8_SB(1, 0), b3, voffB); PG8_STAGE(PG8_SB(1, 1), b3 + hstep, voffB); PG8_STAGE(PG8_SA(1, 0), a3, voffA);
;             PG8_WAIT_V(8); PG8_WAIT_L(0); PG8_BAR; PG8_MMA(1, 0, At, B0); PG8_MMA(1, 1, At, B1); PG8_BAR; PG8_SCHED;
	v_mfma_f32_16x16x32_bf16 v[60:63], v[128:131], v[168:171], v[60:63]
	v_mfma_f32_16x16x32_bf16 v[56:59], v[136:139], v[168:171], v[56:59]
	v_mfma_f32_16x16x32_bf16 v[52:55], v[128:131], v[176:179], v[52:55]
	v_mfma_f32_16x16x32_bf16 v[48:51], v[136:139], v[176:179], v[48:51]
	v_mfma_f32_16x16x32_bf16 v[44:47], v[128:131], v[184:187], v[44:47]
	v_mfma_f32_16x16x32_bf16 v[40:43], v[136:139], v[184:187], v[40:43]
	v_mfma_f32_16x16x32_bf16 v[36:39], v[128:131], v[192:195], v[36:39]
	v_mfma_f32_16x16x32_bf16 v[32:35], v[136:139], v[192:195], v[32:35]
	v_mfma_f32_16x16x32_bf16 v[60:63], v[132:135], v[172:175], v[60:63]
	v_mfma_f32_16x16x32_bf16 v[56:59], v[140:143], v[172:175], v[56:59]
	v_mfma_f32_16x16x32_bf16 v[52:55], v[132:135], v[180:183], v[52:55]
	v_mfma_f32_16x16x32_bf16 v[48:51], v[140:143], v[180:183], v[48:51]
	v_mfma_f32_16x16x32_bf16 v[44:47], v[132:135], v[188:191], v[44:47]
	v_mfma_f32_16x16x32_bf16 v[40:43], v[140:143], v[188:191], v[40:43]
	v_mfma_f32_16x16x32_bf16 v[36:39], v[132:135], v[196:199], v[36:39]
	v_mfma_f32_16x16x32_bf16 v[32:35], v[140:143], v[196:199], v[32:35]
	v_mfma_f32_16x16x32_bf16 v[28:31], v[144:147], v[168:171], v[28:31]
	v_mfma_f32_16x16x32_bf16 v[24:27], v[152:155], v[168:171], v[24:27]
	v_mfma_f32_16x16x32_bf16 v[20:23], v[144:147], v[176:179], v[20:23]
	v_mfma_f32_16x16x32_bf16 v[16:19], v[152:155], v[176:179], v[16:19]
	v_mfma_f32_16x16x32_bf16 v[12:15], v[144:147], v[184:187], v[12:15]
	v_mfma_f32_16x16x32_bf16 v[8:11], v[152:155], v[184:187], v[8:11]
	v_mfma_f32_16x16x32_bf16 v[4:7], v[144:147], v[192:195], v[4:7]
	v_mfma_f32_16x16x32_bf16 v[0:3], v[152:155], v[192:195], v[0:3]
	v_mfma_f32_16x16x32_bf16 v[28:31], v[148:151], v[172:175], v[28:31]
	v_mfma_f32_16x16x32_bf16 v[24:27], v[156:159], v[172:175], v[24:27]
	v_mfma_f32_16x16x32_bf16 v[20:23], v[148:151], v[180:183], v[20:23]
	v_mfma_f32_16x16x32_bf16 v[16:19], v[156:159], v[180:183], v[16:19]
	v_mfma_f32_16x16x32_bf16 v[12:15], v[148:151], v[188:191], v[12:15]
	v_mfma_f32_16x16x32_bf16 v[8:11], v[156:159], v[188:191], v[8:11]
	v_mfma_f32_16x16x32_bf16 v[4:7], v[148:151], v[196:199], v[4:7]
	v_mfma_f32_16x16x32_bf16 v[0:3], v[156:159], v[196:199], v[0:3]
	s_barrier
	s_add_i32 s65, 0, 0x18000
	s_add_i32 s57, 0, 0x1c000
	v_add_u32_e32 v204, s65, v206
	v_add_u32_e32 v205, s57, v206
	ds_read_b128 v[128:131], v204
	ds_read_b128 v[132:135], v204 offset:1024
	ds_read_b128 v[136:139], v204 offset:2048
	ds_read_b128 v[140:143], v204 offset:3072
	ds_read_b128 v[144:147], v205
	ds_read_b128 v[148:151], v205 offset:1024
	ds_read_b128 v[152:155], v205 offset:2048
	ds_read_b128 v[156:159], v205 offset:3072
	s_add_u32 s74, s18, 0x14000
	s_addc_u32 s75, s19, 0
	s_mov_b32 m0, s39
	ds_read_b128 v[168:171], v207 offset:32768
	ds_read_b128 v[172:175], v207 offset:33792
	ds_read_b128 v[176:179], v207 offset:34816
	ds_read_b128 v[180:183], v207 offset:35840
	ds_read_b128 v[184:187], v207 offset:36864
	ds_read_b128 v[188:191], v207 offset:37888
	ds_read_b128 v[192:195], v207 offset:38912
	ds_read_b128 v[196:199], v207 offset:39936
	global_load_lds_dwordx4 v160, s[74:75]
	s_mov_b32 m0, s41
	s_nop 0
	global_load_lds_dwordx4 v164, s[74:75]
	s_waitcnt vmcnt(8) lgkmcnt(0)
	s_barrier
	v_mfma_f32_16x16x32_bf16 v[124:127], v[128:131], v[168:171], v[124:127]
	v_mfma_f32_16x16x32_bf16 v[120:123], v[136:139], v[168:171], v[120:123]
	v_mfma_f32_16x16x32_bf16 v[116:119], v[128:131], v[176:179], v[116:119]
	v_mfma_f32_16x16x32_bf16 v[112:115], v[136:139], v[176:179], v[112:115]
	v_mfma_f32_16x16x32_bf16 v[108:111], v[128:131], v[184:187], v[108:111]
	v_mfma_f32_16x16x32_bf16 v[104:107], v[136:139], v[184:187], v[104:107]
	v_mfma_f32_16x16x32_bf16 v[100:103], v[128:131], v[192:195], v[100:103]
	v_mfma_f32_16x16x32_bf16 v[96:99], v[136:139], v[192:195], v[96:99]
	v_mfma_f32_16x16x32_bf16 v[124:127], v[132:135], v[172:175], v[124:127]
	v_mfma_f32_16x16x32_bf16 v[120:123], v[140:143], v[172:175], v[120:123]
	v_mfma_f32_16x16x32_bf16 v[116:119], v[132:135], v[180:183], v[116:119]
	v_mfma_f32_16x16x32_bf16 v[112:115], v[140:143], v[180:183], v[112:115]
	v_mfma_f32_16x16x32_bf16 v[108:111], v[132:135], v[188:191], v[108:111]
	v_mfma_f32_16x16x32_bf16 v[104:107], v[140:143], v[188:191], v[104:107]
	v_mfma_f32_16x16x32_bf16 v[100:103], v[132:135], v[196:199], v[100:103]
	v_mfma_f32_16x16x32_bf16 v[96:99], v[140:143], v[196:199], v[96:99]
	v_mfma_f32_16x16x32_bf16 v[92:95], v[144:147], v[168:171], v[92:95]
	v_mfma_f32_16x16x32_bf16 v[88:91], v[152:155], v[168:171], v[88:91]
	v_mfma_f32_16x16x32_bf16 v[84:87], v[144:147], v[176:179], v[84:87]
	v_mfma_f32_16x16x32_bf16 v[80:83], v[152:155], v[176:179], v[80:83]
	v_mfma_f32_16x16x32_bf16 v[76:79], v[144:147], v[184:187], v[76:79]
	v_mfma_f32_16x16x32_bf16 v[72:75], v[152:155], v[184:187], v[72:75]
	v_mfma_f32_16x16x32_bf16 v[68:71], v[144:147], v[192:195], v[68:71]
	v_mfma_f32_16x16x32_bf16 v[64:67], v[152:155], v[192:195], v[64:67]
	v_mfma_f32_16x16x32_bf16 v[92:95], v[148:151], v[172:175], v[92:95]
	v_mfma_f32_16x16x32_bf16 v[88:91], v[156:159], v[172:175], v[88:91]
	v_mfma_f32_16x16x32_bf16 v[84:87], v[148:151], v[180:183], v[84:87]
	v_mfma_f32_16x16x32_bf16 v[80:83], v[156:159], v[180:183], v[80:83]
	v_mfma_f32_16x16x32_bf16 v[76:79], v[148:151], v[188:191], v[76:79]
	v_mfma_f32_16x16x32_bf16 v[72:75], v[156:159], v[188:191], v[72:75]
	v_mfma_f32_16x16x32_bf16 v[68:71], v[148:151], v[196:199], v[68:71]
	v_mfma_f32_16x16x32_bf16 v[64:67], v[156:159], v[196:199], v[64:67]
	s_barrier
; #define PG8_STAGE(bufoff, gbase, voff) do { _Pragma("unroll") for (int _i = 0; _i < 2; ++_i) \
;         __builtin_amdgcn_global_load_lds((const unsigned*)((const char*)(gbase) + (voff)[_i]), (PG8_LAS unsigned*)(lds + (bufoff) + ldsw + _i * 8192), 16, 0, 0); } while (0)
; #define PG8_LDA(dst, b, h) do { _Pragma("unroll") for (int m = 0; m < 4; ++m) _Pragma("unroll") for (int k = 0; k < 2; ++k) dst[m][k] = *(const PG8_LAS bf16x8*)(lds + PG8_SA(b, h) + aoff + m * 2048 + k * 1024); } while (0)
; #define PG8_LDB(dst, b, h) do { _Pragma("unroll") for (int n = 0; n < 2; ++n) _Pragma("unroll") for (int k = 0; k < 2; ++k) dst[n][k] = *(const PG8_LAS bf16x8*)(lds + PG8_SB(b, h) + boff + n * 2048 + k * 1024); } while (0)
; #define PG8_MMA(ai, bj, At, Bt) do { __builtin_amdgcn_s_setprio(1); _Pragma("unroll") for (int m = 0; m < 4; ++m) _Pragma("unroll") for (int n = 0; n < 2; ++n) _Pragma("unroll") for (int k = 0; k < 2; ++k) \
;         acc[ai][bj][m][n] = __builtin_amdgcn_mfma_f32_16x16x32_bf16(Bt[n][k], At[m][k], acc[ai][bj][m][n], 0, 0, 0); __builtin_amdgcn_s_setprio(0); } while (0)
; #define PG8_WAIT_V(n) asm volatile("s_waitcnt vmcnt(" #n ")" ::: "memory")
; template <class Epi, class Sched, bool ALIGN_EPI = false, bool SP2 = false>
; __device__ __forceinline__ void gemm_phase(PG8_LAS unsigned char* lds, const Gemm g, const Sched& S, const Epi& E) {
;     ...
;             PG8_LDB(B0, 0, 0); PG8_LDB(B1, 0, 1); PG8_SCHED; PG8_LDA(At, 0, 0); PG8_STAGE(PG8_SA(1, 1), a1 + hstep, voffA);
;             PG8_WAIT_V(8); PG8_WAIT_L(0); PG8_BAR; PG8_MMA(0, 0, At, B0); PG8_MMA(0, 1, At, B1); PG8_BAR; PG8_SCHED;
;             PG8_LDA(At, 0, 1); PG8_STAGE(PG8_SB(0, 0), b2, voffB); PG8_STAGE(PG8_SB(0, 1), b2 + hstep, voffB); PG8_STAGE(PG8_SA(0, 0), a2, voffA);
;             PG8_WAIT_V(8); PG8_WAIT_L(0); PG8_BAR; PG8_MMA(1, 0, At, B0); PG8_MMA(1, 1, At, B1); PG8_BAR; PG8_SCHED;
;             PG8_LDB(B0, 1, 0); PG8_LDB(B1, 1, 1); PG8_SCHED; PG8_LDA(At, 1, 0); PG8_STAGE(PG8_SA(0, 1), a2 + hstep, voffA);
;             PG8_WAIT_V(8); PG8_WAIT_L(0); PG8_BAR; PG8_MMA(0, 0, At, B0); PG8_MMA(0, 1, At, B1); PG8_BAR; PG8_SCHED;
;             PG8_LDA(At, 1, 1); PG8_STAGE(PG8_SB(1, 0), b3, voffB); PG8_STAGE(PG8_SB(1, 1), b3 + hstep, voffB); PG8_STAGE(PG8_SA(1, 0), a3, voffA);
;             PG8_WAIT_V(8); PG8_WAIT_L(0); PG8_BAR; PG8_MMA(1, 0, At, B0); PG8_MMA(1, 1, At, B1); PG8_BAR; PG8_SCHED;
	s_add_u32 s74, s66, 0x18000
	s_addc_u32 s75, s67, 0
	s_add_i32 s65, s65, s30
	s_add_i32 s40, s65, 0x2000
	s_mov_b32 m0, s65
	s_add_u32 s66, s66, 0x1c000
	ds_read_b128 v[168:171], v207 offset:49152
	ds_read_b128 v[172:175], v207 offset:50176
	ds_read_b128 v[176:179], v207 offset:51200
	ds_read_b128 v[180:183], v207 offset:52224
	ds_read_b128 v[184:187], v207 offset:53248
	ds_read_b128 v[188:191], v207 offset:54272
	ds_read_b128 v[192:195], v207 offset:55296
	ds_read_b128 v[196:199], v207 offset:56320
	global_load_lds_dwordx4 v162, s[74:75]
	s_mov_b32 m0, s40
	s_addc_u32 s67, s67, 0
	s_add_i32 s57, s57, s30
	global_load_lds_dwordx4 v166, s[74:75]
	s_mov_b32 m0, s57
	s_add_i32 s61, s57, 0x2000
	global_load_lds_dwordx4 v162, s[66:67]
	s_mov_b32 m0, s61
	s_nop 0
	global_load_lds_dwordx4 v166, s[66:67]
	s_mov_b32 m0, s51
	s_nop 0
	global_load_lds_dwordx4 v160, s[72:73]
	s_mov_b32 m0, s52
	s_nop 0
	global_load_lds_dwordx4 v164, s[72:73]
	s_waitcnt vmcnt(8) lgkmcnt(0)
	s_barrier
	v_mfma_f32_16x16x32_bf16 v[60:63], v[128:131], v[168:171], v[60:63]
	v_mfma_f32_16x16x32_bf16 v[56:59], v[136:139], v[168:171], v[56:59]
	v_mfma_f32_16x16x32_bf16 v[52:55], v[128:131], v[176:179], v[52:55]
	v_mfma_f32_16x16x32_bf16 v[48:51], v[136:139], v[176:179], v[48:51]
	v_mfma_f32_16x16x32_bf16 v[44:47], v[128:131], v[184:187], v[44:47]
	v_mfma_f32_16x16x32_bf16 v[40:43], v[136:139], v[184:187], v[40:43]
	v_mfma_f32_16x16x32_bf16 v[36:39], v[128:131], v[192:195], v[36:39]
	v_mfma_f32_16x16x32_bf16 v[32:35], v[136:139], v[192:195], v[32:35]
	v_mfma_f32_16x16x32_bf16 v[60:63], v[132:135], v[172:175], v[60:63]
	v_mfma_f32_16x16x32_bf16 v[56:59], v[140:143], v[172:175], v[56:59]
	v_mfma_f32_16x16x32_bf16 v[52:55], v[132:135], v[180:183], v[52:55]
	v_mfma_f32_16x16x32_bf16 v[48:51], v[140:143], v[180:183], v[48:51]
	v_mfma_f32_16x16x32_bf16 v[44:47], v[132:135], v[188:191], v[44:47]
	v_mfma_f32_16x16x32_bf16 v[40:43], v[140:143], v[188:191], v[40:43]
	v_mfma_f32_16x16x32_bf16 v[36:39], v[132:135], v[196:199], v[36:39]
	v_mfma_f32_16x16x32_bf16 v[32:35], v[140:143], v[196:199], v[32:35]
	v_mfma_f32_16x16x32_bf16 v[28:31], v[144:147], v[168:171], v[28:31]
	v_mfma_f32_16x16x32_bf16 v[24:27], v[152:155], v[168:171], v[24:27]
	v_mfma_f32_16x16x32_bf16 v[20:23], v[144:147], v[176:179], v[20:23]
	v_mfma_f32_16x16x32_bf16 v[16:19], v[152:155], v[176:179], v[16:19]
	v_mfma_f32_16x16x32_bf16 v[12:15], v[144:147], v[184:187], v[12:15]
	v_mfma_f32_16x16x32_bf16 v[8:11], v[152:155], v[184:187], v[8:11]
	v_mfma_f32_16x16x32_bf16 v[4:7], v[144:147], v[192:195], v[4:7]
	v_mfma_f32_16x16x32_bf16 v[0:3], v[152:155], v[192:195], v[0:3]
	v_mfma_f32_16x16x32_bf16 v[28:31], v[148:151], v[172:175], v[28:31]
	v_mfma_f32_16x16x32_bf16 v[24:27], v[156:159], v[172:175], v[24:27]
	v_mfma_f32_16x16x32_bf16 v[20:23], v[148:151], v[180:183], v[20:23]
	v_mfma_f32_16x16x32_bf16 v[16:19], v[156:159], v[180:183], v[16:19]
	v_mfma_f32_16x16x32_bf16 v[12:15], v[148:151], v[188:191], v[12:15]
	v_mfma_f32_16x16x32_bf16 v[8:11], v[156:159], v[188:191], v[8:11]
	v_mfma_f32_16x16x32_bf16 v[4:7], v[148:151], v[196:199], v[4:7]
	v_mfma_f32_16x16x32_bf16 v[0:3], v[156:159], v[196:199], v[0:3]
	s_barrier
	ds_read_b128 v[128:131], v202
	ds_read_b128 v[132:135], v202 offset:1024
	ds_read_b128 v[136:139], v202 offset:2048
	ds_read_b128 v[140:143], v202 offset:3072
	ds_read_b128 v[144:147], v203
	ds_read_b128 v[148:151], v203 offset:1024
	ds_read_b128 v[152:155], v203 offset:2048
	ds_read_b128 v[156:159], v203 offset:3072
	s_add_u32 s66, s70, 0x8000
	s_addc_u32 s67, s71, 0
	s_add_u32 s18, s18, 0x1c000
	s_addc_u32 s19, s19, 0
	s_mov_b32 m0, s64
	ds_read_b128 v[168:171], v207
	ds_read_b128 v[172:175], v207 offset:1024
	ds_read_b128 v[176:179], v207 offset:2048
	ds_read_b128 v[180:183], v207 offset:3072
	ds_read_b128 v[184:187], v207 offset:4096
	ds_read_b128 v[188:191], v207 offset:5120
	ds_read_b128 v[192:195], v207 offset:6144
	ds_read_b128 v[196:199], v207 offset:7168
	global_load_lds_dwordx4 v160, s[18:19]
	s_mov_b32 m0, s5
	s_nop 0
	global_load_lds_dwordx4 v164, s[18:19]
	s_waitcnt vmcnt(8) lgkmcnt(0)
	s_barrier
	v_mfma_f32_16x16x32_bf16 v[124:127], v[128:131], v[168:171], v[124:127]
	v_mfma_f32_16x16x32_bf16 v[120:123], v[136:139], v[168:171], v[120:123]
	v_mfma_f32_16x16x32_bf16 v[116:119], v[128:131], v[176:179], v[116:119]
	v_mfma_f32_16x16x32_bf16 v[112:115], v[136:139], v[176:179], v[112:115]
	v_mfma_f32_16x16x32_bf16 v[108:111], v[128:131], v[184:187], v[108:111]
	v_mfma_f32_16x16x32_bf16 v[104:107], v[136:139], v[184:187], v[104:107]
	v_mfma_f32_16x16x32_bf16 v[100:103], v[128:131], v[192:195], v[100:103]
	v_mfma_f32_16x16x32_bf16 v[96:99], v[136:139], v[192:195], v[96:99]
	v_mfma_f32_16x16x32_bf16 v[124:127], v[132:135], v[172:175], v[124:127]
	v_mfma_f32_16x16x32_bf16 v[120:123], v[140:143], v[172:175], v[120:123]
	v_mfma_f32_16x16x32_bf16 v[116:119], v[132:135], v[180:183], v[116:119]
	v_mfma_f32_16x16x32_bf16 v[112:115], v[140:143], v[180:183], v[112:115]
	v_mfma_f32_16x16x32_bf16 v[108:111], v[132:135], v[188:191], v[108:111]
	v_mfma_f32_16x16x32_bf16 v[104:107], v[140:143], v[188:191], v[104:107]
	v_mfma_f32_16x16x32_bf16 v[100:103], v[132:135], v[196:199], v[100:103]
	v_mfma_f32_16x16x32_bf16 v[96:99], v[140:143], v[196:199], v[96:99]
	v_mfma_f32_16x16x32_bf16 v[92:95], v[144:147], v[168:171], v[92:95]
	v_mfma_f32_16x16x32_bf16 v[88:91], v[152:155], v[168:171], v[88:91]
	v_mfma_f32_16x16x32_bf16 v[84:87], v[144:147], v[176:179], v[84:87]
	v_mfma_f32_16x16x32_bf16 v[80:83], v[152:155], v[176:179], v[80:83]
	v_mfma_f32_16x16x32_bf16 v[76:79], v[144:147], v[184:187], v[76:79]
	v_mfma_f32_16x16x32_bf16 v[72:75], v[152:155], v[184:187], v[72:75]
	v_mfma_f32_16x16x32_bf16 v[68:71], v[144:147], v[192:195], v[68:71]
	v_mfma_f32_16x16x32_bf16 v[64:67], v[152:155], v[192:195], v[64:67]
	v_mfma_f32_16x16x32_bf16 v[92:95], v[148:151], v[172:175], v[92:95]
	v_mfma_f32_16x16x32_bf16 v[88:91], v[156:159], v[172:175], v[88:91]
	v_mfma_f32_16x16x32_bf16 v[84:87], v[148:151], v[180:183], v[84:87]
	v_mfma_f32_16x16x32_bf16 v[80:83], v[156:159], v[180:183], v[80:83]
	v_mfma_f32_16x16x32_bf16 v[76:79], v[148:151], v[188:191], v[76:79]
	v_mfma_f32_16x16x32_bf16 v[72:75], v[156:159], v[188:191], v[72:75]
	v_mfma_f32_16x16x32_bf16 v[68:71], v[148:151], v[196:199], v[68:71]
	v_mfma_f32_16x16x32_bf16 v[64:67], v[156:159], v[196:199], v[64:67]
	s_barrier
; #define PG8_STAGE(bufoff, gbase, voff) do { _Pragma("unroll") for (int _i = 0; _i < 2; ++_i) \
;         __builtin_amdgcn_global_load_lds((const unsigned*)((const char*)(gbase) + (voff)[_i]), (PG8_LAS unsigned*)(lds + (bufoff) + ldsw + _i * 8192), 16, 0, 0); } while (0)
; #define PG8_LDA(dst, b, h) do { _Pragma("unroll") for (int m = 0; m < 4; ++m) _Pragma("unroll") for (int k = 0; k < 2; ++k) dst[m][k] = *(const PG8_LAS bf16x8*)(lds + PG8_SA(b, h) + aoff + m * 2048 + k * 1024); } while (0)
; #define PG8_LDB(dst, b, h) do { _Pragma("unroll") for (int n = 0; n < 2; ++n) _Pragma("unroll") for (int k = 0; k < 2; ++k) dst[n][k] = *(const PG8_LAS bf16x8*)(lds + PG8_SB(b, h) + boff + n * 2048 + k * 1024); } while (0)
; #define PG8_MMA(ai, bj, At, Bt) do { __builtin_amdgcn_s_setprio(1); _Pragma("unroll") for (int m = 0; m < 4; ++m) _Pragma("unroll") for (int n = 0; n < 2; ++n) _Pragma("unroll") for (int k = 0; k < 2; ++k) \
;         acc[ai][bj][m][n] = __builtin_amdgcn_mfma_f32_16x16x32_bf16(Bt[n][k], At[m][k], acc[ai][bj][m][n], 0, 0, 0); __builtin_amdgcn_s_setprio(0); } while (0)
; #define PG8_WAIT_V(n) asm volatile("s_waitcnt vmcnt(" #n ")" ::: "memory")
; template <class Epi, class Sched, bool ALIGN_EPI = false, bool SP2 = false>
; __device__ __forceinline__ void gemm_phase(PG8_LAS unsigned char* lds, const Gemm g, const Sched& S, const Epi& E) {
;     ...
;             PG8_LDB(B0, 0, 0); PG8_LDB(B1, 0, 1); PG8_SCHED; PG8_LDA(At, 0, 0); PG8_STAGE(PG8_SA(1, 1), a1 + hstep, voffA);
;             PG8_WAIT_V(8); PG8_WAIT_L(0); PG8_BAR; PG8_MMA(0, 0, At, B0); PG8_MMA(0, 1, At, B1); PG8_BAR; PG8_SCHED;
;             PG8_LDA(At, 0, 1); PG8_STAGE(PG8_SB(0, 0), b2, voffB); PG8_STAGE(PG8_SB(0, 1), b2 + hstep, voffB); PG8_STAGE(PG8_SA(0, 0), a2, voffA);
;             PG8_WAIT_V(8); PG8_WAIT_L(0); PG8_BAR; PG8_MMA(1, 0, At, B0); PG8_MMA(1, 1, At, B1); PG8_BAR; PG8_SCHED;
;             PG8_LDB(B0, 1, 0); PG8_LDB(B1, 1, 1); PG8_SCHED; PG8_LDA(At, 1, 0); PG8_STAGE(PG8_SA(0, 1), a2 + hstep, voffA);
;             PG8_WAIT_V(8); PG8_WAIT_L(0); PG8_BAR; PG8_MMA(0, 0, At, B0); PG8_MMA(0, 1, At, B1); PG8_BAR; PG8_SCHED;
;             PG8_LDA(At, 1, 1); PG8_STAGE(PG8_SB(1, 0), b3, voffB); PG8_STAGE(PG8_SB(1, 1), b3 + hstep, voffB); PG8_STAGE(PG8_SA(1, 0), a3, voffA);
;             PG8_WAIT_V(8); PG8_WAIT_L(0); PG8_BAR; PG8_MMA(1, 0, At, B0); PG8_MMA(1, 1, At, B1); PG8_BAR; PG8_SCHED;
	s_mov_b32 m0, s59
	s_add_u32 s18, s68, 0x4000
	ds_read_b128 v[168:171], v207 offset:16384
	ds_read_b128 v[172:175], v207 offset:17408
	ds_read_b128 v[176:179], v207 offset:18432
	ds_read_b128 v[180:183], v207 offset:19456
	ds_read_b128 v[184:187], v207 offset:20480
	ds_read_b128 v[188:191], v207 offset:21504
	ds_read_b128 v[192:195], v207 offset:22528
	ds_read_b128 v[196:199], v207 offset:23552
	global_load_lds_dwordx4 v162, s[68:69]
	s_mov_b32 m0, s11
	s_addc_u32 s19, s69, 0
	global_load_lds_dwordx4 v166, s[68:69]
	s_mov_b32 m0, s13
	s_nop 0
	global_load_lds_dwordx4 v162, s[18:19]
	s_mov_b32 m0, s21
	s_nop 0
	global_load_lds_dwordx4 v166, s[18:19]
	s_mov_b32 m0, s33
	s_nop 0
	global_load_lds_dwordx4 v160, s[70:71]
	s_mov_b32 m0, s37
	s_nop 0
	global_load_lds_dwordx4 v164, s[70:71]
	s_waitcnt vmcnt(8) lgkmcnt(0)
	s_barrier
	v_mfma_f32_16x16x32_bf16 v[60:63], v[128:131], v[168:171], v[60:63]
	v_mfma_f32_16x16x32_bf16 v[56:59], v[136:139], v[168:171], v[56:59]
	v_mfma_f32_16x16x32_bf16 v[52:55], v[128:131], v[176:179], v[52:55]
	v_mfma_f32_16x16x32_bf16 v[48:51], v[136:139], v[176:179], v[48:51]
	v_mfma_f32_16x16x32_bf16 v[44:47], v[128:131], v[184:187], v[44:47]
	v_mfma_f32_16x16x32_bf16 v[40:43], v[136:139], v[184:187], v[40:43]
	v_mfma_f32_16x16x32_bf16 v[36:39], v[128:131], v[192:195], v[36:39]
	v_mfma_f32_16x16x32_bf16 v[32:35], v[136:139], v[192:195], v[32:35]
	v_mfma_f32_16x16x32_bf16 v[60:63], v[132:135], v[172:175], v[60:63]
	v_mfma_f32_16x16x32_bf16 v[56:59], v[140:143], v[172:175], v[56:59]
	v_mfma_f32_16x16x32_bf16 v[52:55], v[132:135], v[180:183], v[52:55]
	v_mfma_f32_16x16x32_bf16 v[48:51], v[140:143], v[180:183], v[48:51]
	v_mfma_f32_16x16x32_bf16 v[44:47], v[132:135], v[188:191], v[44:47]
	v_mfma_f32_16x16x32_bf16 v[40:43], v[140:143], v[188:191], v[40:43]
	v_mfma_f32_16x16x32_bf16 v[36:39], v[132:135], v[196:199], v[36:39]
	v_mfma_f32_16x16x32_bf16 v[32:35], v[140:143], v[196:199], v[32:35]
	v_mfma_f32_16x16x32_bf16 v[28:31], v[144:147], v[168:171], v[28:31]
	v_mfma_f32_16x16x32_bf16 v[24:27], v[152:155], v[168:171], v[24:27]
	v_mfma_f32_16x16x32_bf16 v[20:23], v[144:147], v[176:179], v[20:23]
	v_mfma_f32_16x16x32_bf16 v[16:19], v[152:155], v[176:179], v[16:19]
	v_mfma_f32_16x16x32_bf16 v[12:15], v[144:147], v[184:187], v[12:15]
	v_mfma_f32_16x16x32_bf16 v[8:11], v[152:155], v[184:187], v[8:11]
	v_mfma_f32_16x16x32_bf16 v[4:7], v[144:147], v[192:195], v[4:7]
	v_mfma_f32_16x16x32_bf16 v[0:3], v[152:155], v[192:195], v[0:3]
	v_mfma_f32_16x16x32_bf16 v[28:31], v[148:151], v[172:175], v[28:31]
	v_mfma_f32_16x16x32_bf16 v[24:27], v[156:159], v[172:175], v[24:27]
	v_mfma_f32_16x16x32_bf16 v[20:23], v[148:151], v[180:183], v[20:23]
	v_mfma_f32_16x16x32_bf16 v[16:19], v[156:159], v[180:183], v[16:19]
	v_mfma_f32_16x16x32_bf16 v[12:15], v[148:151], v[188:191], v[12:15]
	v_mfma_f32_16x16x32_bf16 v[8:11], v[156:159], v[188:191], v[8:11]
	v_mfma_f32_16x16x32_bf16 v[4:7], v[148:151], v[196:199], v[4:7]
	v_mfma_f32_16x16x32_bf16 v[0:3], v[156:159], v[196:199], v[0:3]
	s_barrier
	ds_read_b128 v[128:131], v204
	ds_read_b128 v[132:135], v204 offset:1024
	ds_read_b128 v[136:139], v204 offset:2048
	ds_read_b128 v[140:143], v204 offset:3072
	ds_read_b128 v[144:147], v205
	ds_read_b128 v[148:151], v205 offset:1024
	ds_read_b128 v[152:155], v205 offset:2048
	ds_read_b128 v[156:159], v205 offset:3072
	s_add_u32 s18, s70, 0x4000
	s_addc_u32 s19, s71, 0
	s_mov_b32 m0, s39
	ds_read_b128 v[168:171], v207 offset:32768
	ds_read_b128 v[172:175], v207 offset:33792
	ds_read_b128 v[176:179], v207 offset:34816
	ds_read_b128 v[180:183], v207 offset:35840
	ds_read_b128 v[184:187], v207 offset:36864
	ds_read_b128 v[188:191], v207 offset:37888
	ds_read_b128 v[192:195], v207 offset:38912
	ds_read_b128 v[196:199], v207 offset:39936
	global_load_lds_dwordx4 v160, s[18:19]
	s_mov_b32 m0, s41
	s_nop 0
	global_load_lds_dwordx4 v164, s[18:19]
	s_waitcnt vmcnt(8) lgkmcnt(0)
	s_barrier
; #define PG8_STAGE(bufoff, gbase, voff) do { _Pragma("unroll") for (int _i = 0; _i < 2; ++_i) \
;         __builtin_amdgcn_global_load_lds((const unsigned*)((const char*)(gbase) + (voff)[_i]), (PG8_LAS unsigned*)(lds + (bufoff) + ldsw + _i * 8192), 16, 0, 0); } while (0)
; #define PG8_LDA(dst, b, h) do { _Pragma("unroll") for (int m = 0; m < 4; ++m) _Pragma("unroll") for (int k = 0; k < 2; ++k) dst[m][k] = *(const PG8_LAS bf16x8*)(lds + PG8_SA(b, h) + aoff + m * 2048 + k * 1024); } while (0)
; #define PG8_LDB(dst, b, h) do { _Pragma("unroll") for (int n = 0; n < 2; ++n) _Pragma("unroll") for (int k = 0; k < 2; ++k) dst[n][k] = *(const PG8_LAS bf16x8*)(lds + PG8_SB(b, h) + boff + n * 2048 + k * 1024); } while (0)
; #define PG8_WAIT_V(n) asm volatile("s_waitcnt vmcnt(" #n ")" ::: "memory")
; #define PG8_WAIT_L(n) asm volatile("s_waitcnt lgkmcnt(" #n ")" ::: "memory")
; #define PG8_BAR __builtin_amdgcn_s_barrier()
; template <class Epi, class Sched, bool ALIGN_EPI = false, bool SP2 = false>
; __device__ __forceinline__ void gemm_phase(PG8_LAS unsigned char* lds, const Gemm g, const Sched& S, const Epi& E) {
;     ...
;             PG8_LDB(B0, 0, 0); PG8_LDB(B1, 0, 1); PG8_SCHED; PG8_LDA(At, 0, 0); PG8_STAGE(PG8_SA(1, 1), a1 + hstep, voffA);
;             PG8_WAIT_V(8); PG8_WAIT_L(0); PG8_BAR; PG8_MMA(0, 0, At, B0); PG8_MMA(0, 1, At, B1); PG8_BAR; PG8_SCHED;
;             PG8_LDA(At, 0, 1); PG8_STAGE(PG8_SB(0, 0), b2, voffB); PG8_STAGE(PG8_SB(0, 1), b2 + hstep, voffB); PG8_STAGE(PG8_SA(0, 0), a2, voffA);
;             PG8_WAIT_V(8); PG8_WAIT_L(0); PG8_BAR; PG8_MMA(1, 0, At, B0); PG8_MMA(1, 1, At, B1); PG8_BAR; PG8_SCHED;
;             PG8_LDB(B0, 1, 0); PG8_LDB(B1, 1, 1); PG8_SCHED; PG8_LDA(At, 1, 0); PG8_STAGE(PG8_SA(0, 1), a2 + hstep, voffA);
;             PG8_WAIT_V(8); PG8_WAIT_L(0); PG8_BAR; PG8_MMA(0, 0, At, B0); PG8_MMA(0, 1, At, B1); PG8_BAR; PG8_SCHED;
;             PG8_LDA(At, 1, 1); PG8_STAGE(PG8_SB(1, 0), b3, voffB); PG8_STAGE(PG8_SB(1, 1), b3 + hstep, voffB); PG8_STAGE(PG8_SA(1, 0), a3, voffA);
;             PG8_WAIT_V(8); PG8_WAIT_L(0); PG8_BAR; PG8_MMA(1, 0, At, B0); PG8_MMA(1, 1, At, B1); PG8_BAR; PG8_SCHED;
;     ...
;         if constexpr (ALIGN_EPI) { if (wr == 0) PG8_BAR; }
;         const bool keep = Epi::keep_acc(cur);
;         if constexpr (!Epi::AFTER_DRAIN) { if (!keep) E(acc, cur, wr, wc, fr, fq); S.done(cur); }
	v_mfma_f32_16x16x32_bf16 v[124:127], v[128:131], v[168:171], v[124:127]
	v_mfma_f32_16x16x32_bf16 v[120:123], v[136:139], v[168:171], v[120:123]
	v_mfma_f32_16x16x32_bf16 v[116:119], v[128:131], v[176:179], v[116:119]
	v_mfma_f32_16x16x32_bf16 v[112:115], v[136:139], v[176:179], v[112:115]
	v_mfma_f32_16x16x32_bf16 v[108:111], v[128:131], v[184:187], v[108:111]
	v_mfma_f32_16x16x32_bf16 v[104:107], v[136:139], v[184:187], v[104:107]
	v_mfma_f32_16x16x32_bf16 v[100:103], v[128:131], v[192:195], v[100:103]
	v_mfma_f32_16x16x32_bf16 v[96:99], v[136:139], v[192:195], v[96:99]
	v_mfma_f32_16x16x32_bf16 v[124:127], v[132:135], v[172:175], v[124:127]
	v_mfma_f32_16x16x32_bf16 v[120:123], v[140:143], v[172:175], v[120:123]
	v_mfma_f32_16x16x32_bf16 v[116:119], v[132:135], v[180:183], v[116:119]
	v_mfma_f32_16x16x32_bf16 v[112:115], v[140:143], v[180:183], v[112:115]
	v_mfma_f32_16x16x32_bf16 v[108:111], v[132:135], v[188:191], v[108:111]
	v_mfma_f32_16x16x32_bf16 v[104:107], v[140:143], v[188:191], v[104:107]
	v_mfma_f32_16x16x32_bf16 v[100:103], v[132:135], v[196:199], v[100:103]
	v_mfma_f32_16x16x32_bf16 v[96:99], v[140:143], v[196:199], v[96:99]
	v_mfma_f32_16x16x32_bf16 v[92:95], v[144:147], v[168:171], v[92:95]
	v_mfma_f32_16x16x32_bf16 v[88:91], v[152:155], v[168:171], v[88:91]
	v_mfma_f32_16x16x32_bf16 v[84:87], v[144:147], v[176:179], v[84:87]
	v_mfma_f32_16x16x32_bf16 v[80:83], v[152:155], v[176:179], v[80:83]
	v_mfma_f32_16x16x32_bf16 v[76:79], v[144:147], v[184:187], v[76:79]
	v_mfma_f32_16x16x32_bf16 v[72:75], v[152:155], v[184:187], v[72:75]
	v_mfma_f32_16x16x32_bf16 v[68:71], v[144:147], v[192:195], v[68:71]
	v_mfma_f32_16x16x32_bf16 v[64:67], v[152:155], v[192:195], v[64:67]
	v_mfma_f32_16x16x32_bf16 v[92:95], v[148:151], v[172:175], v[92:95]
	v_mfma_f32_16x16x32_bf16 v[88:91], v[156:159], v[172:175], v[88:91]
	v_mfma_f32_16x16x32_bf16 v[84:87], v[148:151], v[180:183], v[84:87]
	v_mfma_f32_16x16x32_bf16 v[80:83], v[156:159], v[180:183], v[80:83]
	v_mfma_f32_16x16x32_bf16 v[76:79], v[148:151], v[188:191], v[76:79]
	v_mfma_f32_16x16x32_bf16 v[72:75], v[156:159], v[188:191], v[72:75]
	v_mfma_f32_16x16x32_bf16 v[68:71], v[148:151], v[196:199], v[68:71]
	v_mfma_f32_16x16x32_bf16 v[64:67], v[156:159], v[196:199], v[64:67]
	s_barrier
	s_add_u32 s18, s68, 0x8000
	s_addc_u32 s19, s69, 0
	s_mov_b32 m0, s65
	ds_read_b128 v[168:171], v207 offset:49152
	ds_read_b128 v[172:175], v207 offset:50176
	ds_read_b128 v[176:179], v207 offset:51200
	ds_read_b128 v[180:183], v207 offset:52224
	ds_read_b128 v[184:187], v207 offset:53248
	ds_read_b128 v[188:191], v207 offset:54272
	ds_read_b128 v[192:195], v207 offset:55296
	ds_read_b128 v[196:199], v207 offset:56320
	global_load_lds_dwordx4 v162, s[18:19]
	v_lshl_add_u64 v[200:201], s[18:19], 0, v[166:167]
	s_add_u32 s18, s68, 0xc000
	s_mov_b32 m0, s40
	s_addc_u32 s19, s69, 0
	global_load_lds_dwordx4 v[200:201], off
	s_mov_b32 m0, s57
	s_nop 0
	global_load_lds_dwordx4 v162, s[18:19]
	s_mov_b32 m0, s61
	s_nop 0
	global_load_lds_dwordx4 v166, s[18:19]
	s_mov_b32 m0, s51
	s_nop 0
	global_load_lds_dwordx4 v160, s[66:67]
	s_mov_b32 m0, s52
	s_nop 0
	global_load_lds_dwordx4 v164, s[66:67]
	s_waitcnt vmcnt(8) lgkmcnt(0)
	s_barrier
	v_mfma_f32_16x16x32_bf16 v[60:63], v[128:131], v[168:171], v[60:63]
	v_mfma_f32_16x16x32_bf16 v[56:59], v[136:139], v[168:171], v[56:59]
	v_mfma_f32_16x16x32_bf16 v[52:55], v[128:131], v[176:179], v[52:55]
	v_mfma_f32_16x16x32_bf16 v[48:51], v[136:139], v[176:179], v[48:51]
	v_mfma_f32_16x16x32_bf16 v[44:47], v[128:131], v[184:187], v[44:47]
	v_mfma_f32_16x16x32_bf16 v[40:43], v[136:139], v[184:187], v[40:43]
	v_mfma_f32_16x16x32_bf16 v[36:39], v[128:131], v[192:195], v[36:39]
	v_mfma_f32_16x16x32_bf16 v[32:35], v[136:139], v[192:195], v[32:35]
	v_mfma_f32_16x16x32_bf16 v[60:63], v[132:135], v[172:175], v[60:63]
	v_mfma_f32_16x16x32_bf16 v[56:59], v[140:143], v[172:175], v[56:59]
	v_mfma_f32_16x16x32_bf16 v[52:55], v[132:135], v[180:183], v[52:55]
	v_mfma_f32_16x16x32_bf16 v[48:51], v[140:143], v[180:183], v[48:51]
	v_mfma_f32_16x16x32_bf16 v[44:47], v[132:135], v[188:191], v[44:47]
	v_mfma_f32_16x16x32_bf16 v[40:43], v[140:143], v[188:191], v[40:43]
	v_mfma_f32_16x16x32_bf16 v[36:39], v[132:135], v[196:199], v[36:39]
	v_mfma_f32_16x16x32_bf16 v[32:35], v[140:143], v[196:199], v[32:35]
	v_mfma_f32_16x16x32_bf16 v[28:31], v[144:147], v[168:171], v[28:31]
	v_mfma_f32_16x16x32_bf16 v[24:27], v[152:155], v[168:171], v[24:27]
	v_mfma_f32_16x16x32_bf16 v[20:23], v[144:147], v[176:179], v[20:23]
	v_mfma_f32_16x16x32_bf16 v[16:19], v[152:155], v[176:179], v[16:19]
	v_mfma_f32_16x16x32_bf16 v[12:15], v[144:147], v[184:187], v[12:15]
	v_mfma_f32_16x16x32_bf16 v[8:11], v[152:155], v[184:187], v[8:11]
	v_mfma_f32_16x16x32_bf16 v[4:7], v[144:147], v[192:195], v[4:7]
	v_mfma_f32_16x16x32_bf16 v[0:3], v[152:155], v[192:195], v[0:3]
	v_mfma_f32_16x16x32_bf16 v[28:31], v[148:151], v[172:175], v[28:31]
	v_mfma_f32_16x16x32_bf16 v[24:27], v[156:159], v[172:175], v[24:27]
	v_mfma_f32_16x16x32_bf16 v[20:23], v[148:151], v[180:183], v[20:23]
	v_mfma_f32_16x16x32_bf16 v[16:19], v[156:159], v[180:183], v[16:19]
	v_mfma_f32_16x16x32_bf16 v[12:15], v[148:151], v[188:191], v[12:15]
	v_mfma_f32_16x16x32_bf16 v[8:11], v[156:159], v[188:191], v[8:11]
	v_mfma_f32_16x16x32_bf16 v[4:7], v[148:151], v[196:199], v[4:7]
	v_mfma_f32_16x16x32_bf16 v[0:3], v[156:159], v[196:199], v[0:3]
	s_barrier
	s_andn2_b64 vcc, exec, s[8:9]
	s_cbranch_vccnz .LBB0_907
	s_barrier

; #define PG8_STAGE(bufoff, gbase, voff) do { _Pragma("unroll") for (int _i = 0; _i < 2; ++_i) \
;         __builtin_amdgcn_global_load_lds((const unsigned*)((const char*)(gbase) + (voff)[_i]), (PG8_LAS unsigned*)(lds + (bufoff) + ldsw + _i * 8192), 16, 0, 0); } while (0)
; #define PG8_LDA(dst, b, h) do { _Pragma("unroll") for (int m = 0; m < 4; ++m) _Pragma("unroll") for (int k = 0; k < 2; ++k) dst[m][k] = *(const PG8_LAS bf16x8*)(lds + PG8_SA(b, h) + aoff + m * 2048 + k * 1024); } while (0)
; #define PG8_LDB(dst, b, h) do { _Pragma("unroll") for (int n = 0; n < 2; ++n) _Pragma("unroll") for (int k = 0; k < 2; ++k) dst[n][k] = *(const PG8_LAS bf16x8*)(lds + PG8_SB(b, h) + boff + n * 2048 + k * 1024); } while (0)
; template <class Epi, class Sched, bool ALIGN_EPI = false, bool SP2 = false>
; __device__ __forceinline__ void gemm_phase(PG8_LAS unsigned char* lds, const Gemm g, const Sched& S, const Epi& E) {
;     ...
;         for (int t = 0; t < nt; t += 2) {
;             const bool last = (t == nt - 2);
;             const char* a1 = cA + (size_t)(t + 1) * kstep;
;             const char* a2 = last ? nA : cA + (size_t)(t + 2) * kstep; const char* b2 = last ? nB : cB + (size_t)(t + 2) * kstep;
;             const char* a3 = a2 + kstep; const char* b3 = b2 + kstep;
;             if (last && has_next) S.a_ready(nxt);
;             if constexpr (SP2) {
;             PG8_LDB(B0, 0, 0); PG8_LDB(B1, 0, 1); PG8_SCHED; PG8_LDA(At, 0, 0); PG8_STAGE(PG8_SA(1, 1), a1 + hstep, voffA);
;             PG8_WAIT_V(8); PG8_WAIT_L(0); PG8_BAR; PG8_MMA(0, 0, At, B0); PG8_MMA(0, 1, At, B1); PG8_BAR; PG8_SCHED;
;             PG8_LDA(At, 0, 1); PG8_STAGE(PG8_SB(0, 0), b2, voffB); PG8_STAGE(PG8_SB(0, 1), b2 + hstep, voffB); PG8_STAGE(PG8_SA(0, 0), a2, voffA);
;             PG8_WAIT_V(8); PG8_WAIT_L(0); PG8_BAR; PG8_MMA(1, 0, At, B0); PG8_MMA(1, 1, At, B1); PG8_BAR; PG8_SCHED;
;             PG8_LDB(B0, 1, 0); PG8_LDB(B1, 1, 1); PG8_SCHED; PG8_LDA(At, 1, 0); PG8_STAGE(PG8_SA(0, 1), a2 + hstep, voffA);
;             PG8_WAIT_V(8); PG8_WAIT_L(0); PG8_BAR; PG8_MMA(0, 0, At, B0); PG8_MMA(0, 1, At, B1); PG8_BAR; PG8_SCHED;
;             PG8_LDA(At, 1, 1); PG8_STAGE(PG8_SB(1, 0), b3, voffB); PG8_STAGE(PG8_SB(1, 1), b3 + hstep, voffB); PG8_STAGE(PG8_SA(1, 0), a3, voffA);
;             PG8_WAIT_V(8); PG8_WAIT_L(0); PG8_BAR; PG8_MMA(1, 0, At, B0); PG8_MMA(1, 1, At, B1); PG8_BAR; PG8_SCHED;
.LBB0_1130:
	s_add_u32 s10, s6, 0x4000
	s_addc_u32 s11, s7, 0
	s_cmp_eq_u32 s40, 12
	s_cselect_b32 s86, s9, s10
	s_cselect_b32 s87, s5, s11
	s_cselect_b32 s84, s23, s30
	s_cselect_b32 s85, s22, s37
	s_add_u32 s10, s86, 0x8000
	s_addc_u32 s11, s87, 0
	s_add_i32 s77, 0, 0x10000
	s_add_i32 s79, 0, 0x14000
	v_add_u32_e32 v32, s77, v192
	v_add_u32_e32 v60, s79, v192
	ds_read_b128 v[16:19], v32
	ds_read_b128 v[20:23], v32 offset:1024
	ds_read_b128 v[24:27], v32 offset:2048
	ds_read_b128 v[32:35], v32 offset:3072
	ds_read_b128 v[48:51], v60
	ds_read_b128 v[52:55], v60 offset:1024
	ds_read_b128 v[56:59], v60 offset:2048
	ds_read_b128 v[60:63], v60 offset:3072
	s_add_i32 m0, s33, 0xc000
	ds_read_b128 v[160:163], v193
	ds_read_b128 v[164:167], v193 offset:1024
	ds_read_b128 v[180:183], v193 offset:2048
	ds_read_b128 v[184:187], v193 offset:3072
	ds_read_b128 v[188:191], v193 offset:4096
	ds_read_b128 v[194:197], v193 offset:5120
	ds_read_b128 v[198:201], v193 offset:6144
	ds_read_b128 v[202:205], v193 offset:7168
	global_load_lds_dwordx4 v176, s[6:7]
	s_add_i32 m0, s33, 0xe000
	s_nop 0
	global_load_lds_dwordx4 v178, s[6:7]
	s_waitcnt vmcnt(8) lgkmcnt(0)
	s_barrier
	v_mfma_f32_16x16x32_bf16 v[156:159], v[16:19], v[160:163], v[156:159]
	v_mfma_f32_16x16x32_bf16 v[152:155], v[24:27], v[160:163], v[152:155]
	v_mfma_f32_16x16x32_bf16 v[140:143], v[16:19], v[180:183], v[140:143]
	v_mfma_f32_16x16x32_bf16 v[136:139], v[24:27], v[180:183], v[136:139]
	v_mfma_f32_16x16x32_bf16 v[124:127], v[16:19], v[188:191], v[124:127]
	v_mfma_f32_16x16x32_bf16 v[120:123], v[24:27], v[188:191], v[120:123]
	v_mfma_f32_16x16x32_bf16 v[108:111], v[16:19], v[198:201], v[108:111]
	v_mfma_f32_16x16x32_bf16 v[104:107], v[24:27], v[198:201], v[104:107]
	v_mfma_f32_16x16x32_bf16 v[156:159], v[20:23], v[164:167], v[156:159]
	v_mfma_f32_16x16x32_bf16 v[152:155], v[32:35], v[164:167], v[152:155]
	v_mfma_f32_16x16x32_bf16 v[140:143], v[20:23], v[184:187], v[140:143]
	v_mfma_f32_16x16x32_bf16 v[136:139], v[32:35], v[184:187], v[136:139]
	v_mfma_f32_16x16x32_bf16 v[124:127], v[20:23], v[194:197], v[124:127]
	v_mfma_f32_16x16x32_bf16 v[120:123], v[32:35], v[194:197], v[120:123]
	v_mfma_f32_16x16x32_bf16 v[108:111], v[20:23], v[202:205], v[108:111]
	v_mfma_f32_16x16x32_bf16 v[104:107], v[32:35], v[202:205], v[104:107]
	v_mfma_f32_16x16x32_bf16 v[148:151], v[48:51], v[160:163], v[148:151]
	v_mfma_f32_16x16x32_bf16 v[144:147], v[56:59], v[160:163], v[144:147]
	v_mfma_f32_16x16x32_bf16 v[132:135], v[48:51], v[180:183], v[132:135]
	v_mfma_f32_16x16x32_bf16 v[128:131], v[56:59], v[180:183], v[128:131]
	v_mfma_f32_16x16x32_bf16 v[116:119], v[48:51], v[188:191], v[116:119]
	v_mfma_f32_16x16x32_bf16 v[112:115], v[56:59], v[188:191], v[112:115]
	v_mfma_f32_16x16x32_bf16 v[100:103], v[48:51], v[198:201], v[100:103]
	v_mfma_f32_16x16x32_bf16 v[96:99], v[56:59], v[198:201], v[96:99]
	v_mfma_f32_16x16x32_bf16 v[148:151], v[52:55], v[164:167], v[148:151]
	v_mfma_f32_16x16x32_bf16 v[144:147], v[60:63], v[164:167], v[144:147]
	v_mfma_f32_16x16x32_bf16 v[132:135], v[52:55], v[184:187], v[132:135]
	v_mfma_f32_16x16x32_bf16 v[128:131], v[60:63], v[184:187], v[128:131]
	v_mfma_f32_16x16x32_bf16 v[116:119], v[52:55], v[194:197], v[116:119]
	v_mfma_f32_16x16x32_bf16 v[112:115], v[60:63], v[194:197], v[112:115]
	v_mfma_f32_16x16x32_bf16 v[100:103], v[52:55], v[202:205], v[100:103]
	v_mfma_f32_16x16x32_bf16 v[96:99], v[60:63], v[202:205], v[96:99]
	s_barrier
	s_add_i32 s77, s77, s57
	s_mov_b32 m0, s77
	ds_read_b128 v[160:163], v193 offset:16384
	ds_read_b128 v[164:167], v193 offset:17408
	ds_read_b128 v[180:183], v193 offset:18432
	ds_read_b128 v[184:187], v193 offset:19456
	ds_read_b128 v[188:191], v193 offset:20480
	ds_read_b128 v[194:197], v193 offset:21504
	ds_read_b128 v[198:201], v193 offset:22528
	ds_read_b128 v[202:205], v193 offset:23552
	global_load_lds_dwordx4 v170, s[84:85]
	s_add_i32 m0, s77, 0x2000
	s_add_u32 s88, s84, 0x4000
	s_addc_u32 s89, s85, 0
	s_add_i32 s77, s79, s57
	global_load_lds_dwordx4 v174, s[84:85]
	s_mov_b32 m0, s77
	s_nop 0
	global_load_lds_dwordx4 v170, s[88:89]
	s_add_i32 m0, s77, 0x2000
	s_nop 0
	global_load_lds_dwordx4 v174, s[88:89]
	s_mov_b32 m0, s33
	s_nop 0
	global_load_lds_dwordx4 v168, s[86:87]
	s_mov_b32 m0, s42
	s_nop 0
	global_load_lds_dwordx4 v172, s[86:87]
	s_waitcnt vmcnt(8) lgkmcnt(0)
	s_barrier
	v_mfma_f32_16x16x32_bf16 v[92:95], v[16:19], v[160:163], v[92:95]
	v_mfma_f32_16x16x32_bf16 v[88:91], v[24:27], v[160:163], v[88:91]
	v_mfma_f32_16x16x32_bf16 v[76:79], v[16:19], v[180:183], v[76:79]
	v_mfma_f32_16x16x32_bf16 v[72:75], v[24:27], v[180:183], v[72:75]
	v_mfma_f32_16x16x32_bf16 v[44:47], v[16:19], v[188:191], v[44:47]
	v_mfma_f32_16x16x32_bf16 v[40:43], v[24:27], v[188:191], v[40:43]
	v_mfma_f32_16x16x32_bf16 v[12:15], v[16:19], v[198:201], v[12:15]
	v_mfma_f32_16x16x32_bf16 v[8:11], v[24:27], v[198:201], v[8:11]
	v_mfma_f32_16x16x32_bf16 v[92:95], v[20:23], v[164:167], v[92:95]
	v_mfma_f32_16x16x32_bf16 v[88:91], v[32:35], v[164:167], v[88:91]
	v_mfma_f32_16x16x32_bf16 v[76:79], v[20:23], v[184:187], v[76:79]
	v_mfma_f32_16x16x32_bf16 v[72:75], v[32:35], v[184:187], v[72:75]
	v_mfma_f32_16x16x32_bf16 v[44:47], v[20:23], v[194:197], v[44:47]
	v_mfma_f32_16x16x32_bf16 v[40:43], v[32:35], v[194:197], v[40:43]
	v_mfma_f32_16x16x32_bf16 v[12:15], v[20:23], v[202:205], v[12:15]
	v_mfma_f32_16x16x32_bf16 v[8:11], v[32:35], v[202:205], v[8:11]
	v_mfma_f32_16x16x32_bf16 v[36:39], v[48:51], v[188:191], v[36:39]
	v_mfma_f32_16x16x32_bf16 v[28:31], v[56:59], v[188:191], v[28:31]
	v_mfma_f32_16x16x32_bf16 v[4:7], v[48:51], v[198:201], v[4:7]
	v_mfma_f32_16x16x32_bf16 v[0:3], v[56:59], v[198:201], v[0:3]
	v_mfma_f32_16x16x32_bf16 v[16:19], v[48:51], v[160:163], v[84:87]
	v_mfma_f32_16x16x32_bf16 v[20:23], v[56:59], v[160:163], v[80:83]
	v_mfma_f32_16x16x32_bf16 v[24:27], v[48:51], v[180:183], v[68:71]
	v_mfma_f32_16x16x32_bf16 v[32:35], v[56:59], v[180:183], v[64:67]
	v_mfma_f32_16x16x32_bf16 v[36:39], v[52:55], v[194:197], v[36:39]
	v_mfma_f32_16x16x32_bf16 v[28:31], v[60:63], v[194:197], v[28:31]
	v_mfma_f32_16x16x32_bf16 v[4:7], v[52:55], v[202:205], v[4:7]
	v_mfma_f32_16x16x32_bf16 v[0:3], v[60:63], v[202:205], v[0:3]
	v_mfma_f32_16x16x32_bf16 v[16:19], v[52:55], v[164:167], v[16:19]
	v_mfma_f32_16x16x32_bf16 v[20:23], v[60:63], v[164:167], v[20:23]
	v_mfma_f32_16x16x32_bf16 v[24:27], v[52:55], v[184:187], v[24:27]
	v_mfma_f32_16x16x32_bf16 v[32:35], v[60:63], v[184:187], v[32:35]
	s_barrier
; #define PG8_STAGE(bufoff, gbase, voff) do { _Pragma("unroll") for (int _i = 0; _i < 2; ++_i) \
;         __builtin_amdgcn_global_load_lds((const unsigned*)((const char*)(gbase) + (voff)[_i]), (PG8_LAS unsigned*)(lds + (bufoff) + ldsw + _i * 8192), 16, 0, 0); } while (0)
; #define PG8_LDA(dst, b, h) do { _Pragma("unroll") for (int m = 0; m < 4; ++m) _Pragma("unroll") for (int k = 0; k < 2; ++k) dst[m][k] = *(const PG8_LAS bf16x8*)(lds + PG8_SA(b, h) + aoff + m * 2048 + k * 1024); } while (0)
; #define PG8_LDB(dst, b, h) do { _Pragma("unroll") for (int n = 0; n < 2; ++n) _Pragma("unroll") for (int k = 0; k < 2; ++k) dst[n][k] = *(const PG8_LAS bf16x8*)(lds + PG8_SB(b, h) + boff + n * 2048 + k * 1024); } while (0)
; #define PG8_MMA(ai, bj, At, Bt) do { __builtin_amdgcn_s_setprio(1); _Pragma("unroll") for (int m = 0; m < 4; ++m) _Pragma("unroll") for (int n = 0; n < 2; ++n) _Pragma("unroll") for (int k = 0; k < 2; ++k) \
;         acc[ai][bj][m][n] = __builtin_amdgcn_mfma_f32_16x16x32_bf16(Bt[n][k], At[m][k], acc[ai][bj][m][n], 0, 0, 0); __builtin_amdgcn_s_setprio(0); } while (0)
; template <class Epi, class Sched, bool ALIGN_EPI = false, bool SP2 = false>
; __device__ __forceinline__ void gemm_phase(PG8_LAS unsigned char* lds, const Gemm g, const Sched& S, const Epi& E) {
;     ...
;             PG8_LDB(B0, 0, 0); PG8_LDB(B1, 0, 1); PG8_SCHED; PG8_LDA(At, 0, 0); PG8_STAGE(PG8_SA(1, 1), a1 + hstep, voffA);
;             PG8_WAIT_V(8); PG8_WAIT_L(0); PG8_BAR; PG8_MMA(0, 0, At, B0); PG8_MMA(0, 1, At, B1); PG8_BAR; PG8_SCHED;
;             PG8_LDA(At, 0, 1); PG8_STAGE(PG8_SB(0, 0), b2, voffB); PG8_STAGE(PG8_SB(0, 1), b2 + hstep, voffB); PG8_STAGE(PG8_SA(0, 0), a2, voffA);
;             PG8_WAIT_V(8); PG8_WAIT_L(0); PG8_BAR; PG8_MMA(1, 0, At, B0); PG8_MMA(1, 1, At, B1); PG8_BAR; PG8_SCHED;
;             PG8_LDB(B0, 1, 0); PG8_LDB(B1, 1, 1); PG8_SCHED; PG8_LDA(At, 1, 0); PG8_STAGE(PG8_SA(0, 1), a2 + hstep, voffA);
;             PG8_WAIT_V(8); PG8_WAIT_L(0); PG8_BAR; PG8_MMA(0, 0, At, B0); PG8_MMA(0, 1, At, B1); PG8_BAR; PG8_SCHED;
;             PG8_LDA(At, 1, 1); PG8_STAGE(PG8_SB(1, 0), b3, voffB); PG8_STAGE(PG8_SB(1, 1), b3 + hstep, voffB); PG8_STAGE(PG8_SA(1, 0), a3, voffA);
;             PG8_WAIT_V(8); PG8_WAIT_L(0); PG8_BAR; PG8_MMA(1, 0, At, B0); PG8_MMA(1, 1, At, B1); PG8_BAR; PG8_SCHED;
;     ...
;         if constexpr (ALIGN_EPI) { if (wr == 0) PG8_BAR; }
	s_add_i32 s77, 0, 0x18000
	s_add_i32 s79, 0, 0x1c000
	v_add_u32_e32 v60, s77, v192
	v_add_u32_e32 v64, s79, v192
	ds_read_b128 v[48:51], v60
	ds_read_b128 v[52:55], v60 offset:1024
	ds_read_b128 v[56:59], v60 offset:2048
	ds_read_b128 v[60:63], v60 offset:3072
	ds_read_b128 v[160:163], v64
	ds_read_b128 v[164:167], v64 offset:1024
	ds_read_b128 v[180:183], v64 offset:2048
	ds_read_b128 v[184:187], v64 offset:3072
	s_add_u32 s86, s86, 0x4000
	s_addc_u32 s87, s87, 0
	s_mov_b32 m0, s64
	ds_read_b128 v[64:67], v193 offset:32768
	ds_read_b128 v[68:71], v193 offset:33792
	ds_read_b128 v[80:83], v193 offset:34816
	ds_read_b128 v[84:87], v193 offset:35840
	ds_read_b128 v[188:191], v193 offset:36864
	ds_read_b128 v[194:197], v193 offset:37888
	ds_read_b128 v[198:201], v193 offset:38912
	ds_read_b128 v[202:205], v193 offset:39936
	global_load_lds_dwordx4 v168, s[86:87]
	s_mov_b32 m0, s65
	s_nop 0
	global_load_lds_dwordx4 v172, s[86:87]
	s_waitcnt vmcnt(8) lgkmcnt(0)
	s_barrier
	v_mfma_f32_16x16x32_bf16 v[156:159], v[48:51], v[64:67], v[156:159]
	v_mfma_f32_16x16x32_bf16 v[152:155], v[56:59], v[64:67], v[152:155]
	v_mfma_f32_16x16x32_bf16 v[140:143], v[48:51], v[80:83], v[140:143]
	v_mfma_f32_16x16x32_bf16 v[136:139], v[56:59], v[80:83], v[136:139]
	v_mfma_f32_16x16x32_bf16 v[124:127], v[48:51], v[188:191], v[124:127]
	v_mfma_f32_16x16x32_bf16 v[120:123], v[56:59], v[188:191], v[120:123]
	v_mfma_f32_16x16x32_bf16 v[108:111], v[48:51], v[198:201], v[108:111]
	v_mfma_f32_16x16x32_bf16 v[104:107], v[56:59], v[198:201], v[104:107]
	v_mfma_f32_16x16x32_bf16 v[156:159], v[52:55], v[68:71], v[156:159]
	v_mfma_f32_16x16x32_bf16 v[152:155], v[60:63], v[68:71], v[152:155]
	v_mfma_f32_16x16x32_bf16 v[140:143], v[52:55], v[84:87], v[140:143]
	v_mfma_f32_16x16x32_bf16 v[136:139], v[60:63], v[84:87], v[136:139]
	v_mfma_f32_16x16x32_bf16 v[124:127], v[52:55], v[194:197], v[124:127]
	v_mfma_f32_16x16x32_bf16 v[120:123], v[60:63], v[194:197], v[120:123]
	v_mfma_f32_16x16x32_bf16 v[108:111], v[52:55], v[202:205], v[108:111]
	v_mfma_f32_16x16x32_bf16 v[104:107], v[60:63], v[202:205], v[104:107]
	v_mfma_f32_16x16x32_bf16 v[148:151], v[160:163], v[64:67], v[148:151]
	v_mfma_f32_16x16x32_bf16 v[64:67], v[180:183], v[64:67], v[144:147]
	v_mfma_f32_16x16x32_bf16 v[144:147], v[184:187], v[68:71], v[64:67]
	v_mfma_f32_16x16x32_bf16 v[64:67], v[160:163], v[80:83], v[132:135]
	v_mfma_f32_16x16x32_bf16 v[132:135], v[164:167], v[84:87], v[64:67]
	v_mfma_f32_16x16x32_bf16 v[64:67], v[180:183], v[80:83], v[128:131]
	v_mfma_f32_16x16x32_bf16 v[128:131], v[184:187], v[84:87], v[64:67]
	v_mfma_f32_16x16x32_bf16 v[64:67], v[160:163], v[188:191], v[116:119]
	v_mfma_f32_16x16x32_bf16 v[116:119], v[164:167], v[194:197], v[64:67]
	v_mfma_f32_16x16x32_bf16 v[64:67], v[180:183], v[188:191], v[112:115]
	v_mfma_f32_16x16x32_bf16 v[112:115], v[184:187], v[194:197], v[64:67]
	v_mfma_f32_16x16x32_bf16 v[64:67], v[160:163], v[198:201], v[100:103]
	v_mfma_f32_16x16x32_bf16 v[100:103], v[164:167], v[202:205], v[64:67]
	v_mfma_f32_16x16x32_bf16 v[64:67], v[180:183], v[198:201], v[96:99]
	v_mfma_f32_16x16x32_bf16 v[148:151], v[164:167], v[68:71], v[148:151]
	v_mfma_f32_16x16x32_bf16 v[96:99], v[184:187], v[202:205], v[64:67]
	s_barrier
	s_add_u32 s86, s84, 0x8000
	s_addc_u32 s87, s85, 0
	s_add_i32 s77, s77, s57
	s_mov_b32 m0, s77
	ds_read_b128 v[64:67], v193 offset:49152
	ds_read_b128 v[68:71], v193 offset:50176
	ds_read_b128 v[188:191], v193 offset:51200
	ds_read_b128 v[194:197], v193 offset:52224
	ds_read_b128 v[198:201], v193 offset:53248
	ds_read_b128 v[202:205], v193 offset:54272
	ds_read_b128 v[206:209], v193 offset:55296
	ds_read_b128 v[210:213], v193 offset:56320
	global_load_lds_dwordx4 v170, s[86:87]
	s_add_i32 m0, s77, 0x2000
	s_add_u32 s84, s84, 0xc000
	s_addc_u32 s85, s85, 0
	s_add_i32 s77, s79, s57
	global_load_lds_dwordx4 v174, s[86:87]
	s_mov_b32 m0, s77
	s_nop 0
	global_load_lds_dwordx4 v170, s[84:85]
	s_add_i32 m0, s77, 0x2000
	s_nop 0
	global_load_lds_dwordx4 v174, s[84:85]
	s_mov_b32 m0, s53
	s_nop 0
	global_load_lds_dwordx4 v168, s[10:11]
	s_mov_b32 m0, s27
	s_nop 0
	global_load_lds_dwordx4 v172, s[10:11]
	s_waitcnt vmcnt(8) lgkmcnt(0)
	s_barrier
	v_mfma_f32_16x16x32_bf16 v[80:83], v[48:51], v[64:67], v[92:95]
	v_mfma_f32_16x16x32_bf16 v[92:95], v[52:55], v[68:71], v[80:83]
	v_mfma_f32_16x16x32_bf16 v[80:83], v[56:59], v[64:67], v[88:91]
	v_mfma_f32_16x16x32_bf16 v[76:79], v[48:51], v[188:191], v[76:79]
	v_mfma_f32_16x16x32_bf16 v[72:75], v[56:59], v[188:191], v[72:75]
	v_mfma_f32_16x16x32_bf16 v[44:47], v[48:51], v[198:201], v[44:47]
	v_mfma_f32_16x16x32_bf16 v[40:43], v[56:59], v[198:201], v[40:43]
	v_mfma_f32_16x16x32_bf16 v[12:15], v[48:51], v[206:209], v[12:15]
	v_mfma_f32_16x16x32_bf16 v[8:11], v[56:59], v[206:209], v[8:11]
	v_mfma_f32_16x16x32_bf16 v[88:91], v[60:63], v[68:71], v[80:83]
	v_mfma_f32_16x16x32_bf16 v[76:79], v[52:55], v[194:197], v[76:79]
	v_mfma_f32_16x16x32_bf16 v[72:75], v[60:63], v[194:197], v[72:75]
	v_mfma_f32_16x16x32_bf16 v[44:47], v[52:55], v[202:205], v[44:47]
	v_mfma_f32_16x16x32_bf16 v[40:43], v[60:63], v[202:205], v[40:43]
	v_mfma_f32_16x16x32_bf16 v[12:15], v[52:55], v[210:213], v[12:15]
	v_mfma_f32_16x16x32_bf16 v[8:11], v[60:63], v[210:213], v[8:11]
	v_mfma_f32_16x16x32_bf16 v[16:19], v[160:163], v[64:67], v[16:19]
	v_mfma_f32_16x16x32_bf16 v[84:87], v[164:167], v[68:71], v[16:19]
	v_mfma_f32_16x16x32_bf16 v[16:19], v[180:183], v[64:67], v[20:23]
	v_mfma_f32_16x16x32_bf16 v[80:83], v[184:187], v[68:71], v[16:19]
	v_mfma_f32_16x16x32_bf16 v[16:19], v[160:163], v[188:191], v[24:27]
	v_mfma_f32_16x16x32_bf16 v[68:71], v[164:167], v[194:197], v[16:19]
	v_mfma_f32_16x16x32_bf16 v[16:19], v[180:183], v[188:191], v[32:35]
	v_mfma_f32_16x16x32_bf16 v[64:67], v[184:187], v[194:197], v[16:19]
	v_mfma_f32_16x16x32_bf16 v[16:19], v[160:163], v[198:201], v[36:39]
	v_mfma_f32_16x16x32_bf16 v[36:39], v[164:167], v[202:205], v[16:19]
	v_mfma_f32_16x16x32_bf16 v[16:19], v[180:183], v[198:201], v[28:31]
	v_mfma_f32_16x16x32_bf16 v[4:7], v[160:163], v[206:209], v[4:7]
	v_mfma_f32_16x16x32_bf16 v[0:3], v[180:183], v[206:209], v[0:3]
	v_mfma_f32_16x16x32_bf16 v[28:31], v[184:187], v[202:205], v[16:19]
	v_mfma_f32_16x16x32_bf16 v[4:7], v[164:167], v[210:213], v[4:7]
	v_mfma_f32_16x16x32_bf16 v[0:3], v[184:187], v[210:213], v[0:3]
	s_barrier
	s_add_i32 s40, s40, 2
	s_add_u32 s6, s6, 0x10000
	s_addc_u32 s7, s7, 0
	s_add_u32 s30, s30, 0x10000
	s_addc_u32 s37, s37, 0
	s_cmp_gt_u32 s40, 13
	s_cbranch_scc0 .LBB0_1130
	s_and_b64 vcc, exec, s[70:71]
	s_cbranch_vccz .LBB0_1133
	s_barrier

; #define PG8_STAGE(bufoff, gbase, voff) do { _Pragma("unroll") for (int _i = 0; _i < 2; ++_i) \
;         __builtin_amdgcn_global_load_lds((const unsigned*)((const char*)(gbase) + (voff)[_i]), (PG8_LAS unsigned*)(lds + (bufoff) + ldsw + _i * 8192), 16, 0, 0); } while (0)
; #define PG8_LDA(dst, b, h) do { _Pragma("unroll") for (int m = 0; m < 4; ++m) _Pragma("unroll") for (int k = 0; k < 2; ++k) dst[m][k] = *(const PG8_LAS bf16x8*)(lds + PG8_SA(b, h) + aoff + m * 2048 + k * 1024); } while (0)
; #define PG8_LDB(dst, b, h) do { _Pragma("unroll") for (int n = 0; n < 2; ++n) _Pragma("unroll") for (int k = 0; k < 2; ++k) dst[n][k] = *(const PG8_LAS bf16x8*)(lds + PG8_SB(b, h) + boff + n * 2048 + k * 1024); } while (0)
; #define PG8_MMA(ai, bj, At, Bt) do { __builtin_amdgcn_s_setprio(1); _Pragma("unroll") for (int m = 0; m < 4; ++m) _Pragma("unroll") for (int n = 0; n < 2; ++n) _Pragma("unroll") for (int k = 0; k < 2; ++k) \
;         acc[ai][bj][m][n] = __builtin_amdgcn_mfma_f32_16x16x32_bf16(Bt[n][k], At[m][k], acc[ai][bj][m][n], 0, 0, 0); __builtin_amdgcn_s_setprio(0); } while (0)
; #define PG8_WAIT_V(n) asm volatile("s_waitcnt vmcnt(" #n ")" ::: "memory")
; template <class Epi, class Sched, bool ALIGN_EPI = false, bool SP2 = false>
; __device__ __forceinline__ void gemm_phase(PG8_LAS unsigned char* lds, const Gemm g, const Sched& S, const Epi& E) {
;     ...
;             PG8_LDB(B0, 0, 0); PG8_LDB(B1, 0, 1); PG8_SCHED; PG8_LDA(At, 0, 0); PG8_STAGE(PG8_SA(1, 1), a1 + hstep, voffA);
;             PG8_WAIT_V(8); PG8_WAIT_L(0); PG8_BAR; PG8_MMA(0, 0, At, B0); PG8_MMA(0, 1, At, B1); PG8_BAR; PG8_SCHED;
;             PG8_LDA(At, 0, 1); PG8_STAGE(PG8_SB(0, 0), b2, voffB); PG8_STAGE(PG8_SB(0, 1), b2 + hstep, voffB); PG8_STAGE(PG8_SA(0, 0), a2, voffA);
;             PG8_WAIT_V(8); PG8_WAIT_L(0); PG8_BAR; PG8_MMA(1, 0, At, B0); PG8_MMA(1, 1, At, B1); PG8_BAR; PG8_SCHED;
;             PG8_LDB(B0, 1, 0); PG8_LDB(B1, 1, 1); PG8_SCHED; PG8_LDA(At, 1, 0); PG8_STAGE(PG8_SA(0, 1), a2 + hstep, voffA);
;             PG8_WAIT_V(8); PG8_WAIT_L(0); PG8_BAR; PG8_MMA(0, 0, At, B0); PG8_MMA(0, 1, At, B1); PG8_BAR; PG8_SCHED;
;             PG8_LDA(At, 1, 1); PG8_STAGE(PG8_SB(1, 0), b3, voffB); PG8_STAGE(PG8_SB(1, 1), b3 + hstep, voffB); PG8_STAGE(PG8_SA(1, 0), a3, voffA);
;             PG8_WAIT_V(8); PG8_WAIT_L(0); PG8_BAR; PG8_MMA(1, 0, At, B0); PG8_MMA(1, 1, At, B1); PG8_BAR; PG8_SCHED;
.LBB0_1322:
	s_add_i32 s75, s18, 2
	s_add_u32 s19, s16, 0x4000
	s_addc_u32 s20, s17, 0
	s_cmp_eq_u32 s59, s18
	s_cselect_b32 s64, s0, s19
	s_cselect_b32 s65, s1, s20
	s_cselect_b32 s20, s14, s66
	s_cselect_b32 s21, s15, s67
	s_add_u32 s18, s64, 0x8000
	s_addc_u32 s19, s65, 0
	s_add_i32 s76, 0, 0x10000
	s_add_i32 s78, 0, 0x14000
	v_add_u32_e32 v108, s76, v206
	v_add_u32_e32 v156, s78, v206
	ds_read_b128 v[80:83], v108
	ds_read_b128 v[84:87], v108 offset:1024
	ds_read_b128 v[104:107], v108 offset:2048
	ds_read_b128 v[108:111], v108 offset:3072
	ds_read_b128 v[128:131], v156
	ds_read_b128 v[136:139], v156 offset:1024
	ds_read_b128 v[152:155], v156 offset:2048
	ds_read_b128 v[156:159], v156 offset:3072
	s_add_i32 m0, s41, 0xc000
	ds_read_b128 v[160:163], v207
	ds_read_b128 v[164:167], v207 offset:1024
	ds_read_b128 v[168:171], v207 offset:2048
	ds_read_b128 v[172:175], v207 offset:3072
	ds_read_b128 v[176:179], v207 offset:4096
	ds_read_b128 v[180:183], v207 offset:5120
	ds_read_b128 v[198:201], v207 offset:6144
	ds_read_b128 v[202:205], v207 offset:7168
	global_load_lds_dwordx4 v194, s[16:17]
	s_add_i32 m0, s41, 0xe000
	s_nop 0
	global_load_lds_dwordx4 v196, s[16:17]
	s_waitcnt vmcnt(8) lgkmcnt(0)
	s_barrier
	v_mfma_f32_16x16x32_bf16 v[148:151], v[80:83], v[160:163], v[148:151]
	v_mfma_f32_16x16x32_bf16 v[144:147], v[104:107], v[160:163], v[144:147]
	v_mfma_f32_16x16x32_bf16 v[124:127], v[80:83], v[168:171], v[124:127]
	v_mfma_f32_16x16x32_bf16 v[120:123], v[104:107], v[168:171], v[120:123]
	v_mfma_f32_16x16x32_bf16 v[100:103], v[80:83], v[176:179], v[100:103]
	v_mfma_f32_16x16x32_bf16 v[96:99], v[104:107], v[176:179], v[96:99]
	v_mfma_f32_16x16x32_bf16 v[76:79], v[80:83], v[198:201], v[76:79]
	v_mfma_f32_16x16x32_bf16 v[72:75], v[104:107], v[198:201], v[72:75]
	v_mfma_f32_16x16x32_bf16 v[148:151], v[84:87], v[164:167], v[148:151]
	v_mfma_f32_16x16x32_bf16 v[144:147], v[108:111], v[164:167], v[144:147]
	v_mfma_f32_16x16x32_bf16 v[124:127], v[84:87], v[172:175], v[124:127]
	v_mfma_f32_16x16x32_bf16 v[120:123], v[108:111], v[172:175], v[120:123]
	v_mfma_f32_16x16x32_bf16 v[100:103], v[84:87], v[180:183], v[100:103]
	v_mfma_f32_16x16x32_bf16 v[96:99], v[108:111], v[180:183], v[96:99]
	v_mfma_f32_16x16x32_bf16 v[76:79], v[84:87], v[202:205], v[76:79]
	v_mfma_f32_16x16x32_bf16 v[72:75], v[108:111], v[202:205], v[72:75]
	v_mfma_f32_16x16x32_bf16 v[140:143], v[128:131], v[160:163], v[140:143]
	v_mfma_f32_16x16x32_bf16 v[132:135], v[152:155], v[160:163], v[132:135]
	v_mfma_f32_16x16x32_bf16 v[116:119], v[128:131], v[168:171], v[116:119]
	v_mfma_f32_16x16x32_bf16 v[112:115], v[152:155], v[168:171], v[112:115]
	v_mfma_f32_16x16x32_bf16 v[92:95], v[128:131], v[176:179], v[92:95]
	v_mfma_f32_16x16x32_bf16 v[88:91], v[152:155], v[176:179], v[88:91]
	v_mfma_f32_16x16x32_bf16 v[68:71], v[128:131], v[198:201], v[68:71]
	v_mfma_f32_16x16x32_bf16 v[64:67], v[152:155], v[198:201], v[64:67]
	v_mfma_f32_16x16x32_bf16 v[140:143], v[136:139], v[164:167], v[140:143]
	v_mfma_f32_16x16x32_bf16 v[132:135], v[156:159], v[164:167], v[132:135]
	v_mfma_f32_16x16x32_bf16 v[116:119], v[136:139], v[172:175], v[116:119]
	v_mfma_f32_16x16x32_bf16 v[112:115], v[156:159], v[172:175], v[112:115]
	v_mfma_f32_16x16x32_bf16 v[92:95], v[136:139], v[180:183], v[92:95]
	v_mfma_f32_16x16x32_bf16 v[88:91], v[156:159], v[180:183], v[88:91]
	v_mfma_f32_16x16x32_bf16 v[68:71], v[136:139], v[202:205], v[68:71]
	v_mfma_f32_16x16x32_bf16 v[64:67], v[156:159], v[202:205], v[64:67]
	s_barrier
	s_add_i32 s76, s76, s39
	s_mov_b32 m0, s76
	ds_read_b128 v[160:163], v207 offset:16384
	ds_read_b128 v[164:167], v207 offset:17408
	ds_read_b128 v[168:171], v207 offset:18432
	ds_read_b128 v[172:175], v207 offset:19456
	ds_read_b128 v[176:179], v207 offset:20480
	ds_read_b128 v[180:183], v207 offset:21504
	ds_read_b128 v[198:201], v207 offset:22528
	ds_read_b128 v[202:205], v207 offset:23552
	global_load_lds_dwordx4 v186, s[20:21]
	s_add_i32 m0, s76, 0x2000
	s_add_u32 s76, s20, 0x4000
	s_addc_u32 s77, s21, 0
	s_add_i32 s78, s78, s39
	global_load_lds_dwordx4 v190, s[20:21]
	s_mov_b32 m0, s78
	s_nop 0
	global_load_lds_dwordx4 v186, s[76:77]
	s_add_i32 m0, s78, 0x2000
	s_nop 0
	global_load_lds_dwordx4 v190, s[76:77]
	s_mov_b32 m0, s41
	s_nop 0
	global_load_lds_dwordx4 v184, s[64:65]
	s_mov_b32 m0, s42
	s_nop 0
	global_load_lds_dwordx4 v188, s[64:65]
	s_waitcnt vmcnt(8) lgkmcnt(0)
	s_barrier
	v_mfma_f32_16x16x32_bf16 v[60:63], v[80:83], v[160:163], v[60:63]
	v_mfma_f32_16x16x32_bf16 v[56:59], v[104:107], v[160:163], v[56:59]
	v_mfma_f32_16x16x32_bf16 v[44:47], v[80:83], v[168:171], v[44:47]
	v_mfma_f32_16x16x32_bf16 v[40:43], v[104:107], v[168:171], v[40:43]
	v_mfma_f32_16x16x32_bf16 v[28:31], v[80:83], v[176:179], v[28:31]
	v_mfma_f32_16x16x32_bf16 v[24:27], v[104:107], v[176:179], v[24:27]
	v_mfma_f32_16x16x32_bf16 v[12:15], v[80:83], v[198:201], v[12:15]
	v_mfma_f32_16x16x32_bf16 v[8:11], v[104:107], v[198:201], v[8:11]
	v_mfma_f32_16x16x32_bf16 v[60:63], v[84:87], v[164:167], v[60:63]
	v_mfma_f32_16x16x32_bf16 v[56:59], v[108:111], v[164:167], v[56:59]
	v_mfma_f32_16x16x32_bf16 v[44:47], v[84:87], v[172:175], v[44:47]
	v_mfma_f32_16x16x32_bf16 v[40:43], v[108:111], v[172:175], v[40:43]
	v_mfma_f32_16x16x32_bf16 v[28:31], v[84:87], v[180:183], v[28:31]
	v_mfma_f32_16x16x32_bf16 v[24:27], v[108:111], v[180:183], v[24:27]
	v_mfma_f32_16x16x32_bf16 v[12:15], v[84:87], v[202:205], v[12:15]
	v_mfma_f32_16x16x32_bf16 v[8:11], v[108:111], v[202:205], v[8:11]
	v_mfma_f32_16x16x32_bf16 v[52:55], v[128:131], v[160:163], v[52:55]
	v_mfma_f32_16x16x32_bf16 v[48:51], v[152:155], v[160:163], v[48:51]
	v_mfma_f32_16x16x32_bf16 v[36:39], v[128:131], v[168:171], v[36:39]
	v_mfma_f32_16x16x32_bf16 v[32:35], v[152:155], v[168:171], v[32:35]
	v_mfma_f32_16x16x32_bf16 v[20:23], v[128:131], v[176:179], v[20:23]
	v_mfma_f32_16x16x32_bf16 v[16:19], v[152:155], v[176:179], v[16:19]
	v_mfma_f32_16x16x32_bf16 v[4:7], v[128:131], v[198:201], v[4:7]
	v_mfma_f32_16x16x32_bf16 v[0:3], v[152:155], v[198:201], v[0:3]
	v_mfma_f32_16x16x32_bf16 v[52:55], v[136:139], v[164:167], v[52:55]
	v_mfma_f32_16x16x32_bf16 v[48:51], v[156:159], v[164:167], v[48:51]
	v_mfma_f32_16x16x32_bf16 v[36:39], v[136:139], v[172:175], v[36:39]
	v_mfma_f32_16x16x32_bf16 v[32:35], v[156:159], v[172:175], v[32:35]
	v_mfma_f32_16x16x32_bf16 v[20:23], v[136:139], v[180:183], v[20:23]
	v_mfma_f32_16x16x32_bf16 v[16:19], v[156:159], v[180:183], v[16:19]
	v_mfma_f32_16x16x32_bf16 v[4:7], v[136:139], v[202:205], v[4:7]
	v_mfma_f32_16x16x32_bf16 v[0:3], v[156:159], v[202:205], v[0:3]
	s_barrier
; #define PG8_STAGE(bufoff, gbase, voff) do { _Pragma("unroll") for (int _i = 0; _i < 2; ++_i) \
;         __builtin_amdgcn_global_load_lds((const unsigned*)((const char*)(gbase) + (voff)[_i]), (PG8_LAS unsigned*)(lds + (bufoff) + ldsw + _i * 8192), 16, 0, 0); } while (0)
; #define PG8_LDA(dst, b, h) do { _Pragma("unroll") for (int m = 0; m < 4; ++m) _Pragma("unroll") for (int k = 0; k < 2; ++k) dst[m][k] = *(const PG8_LAS bf16x8*)(lds + PG8_SA(b, h) + aoff + m * 2048 + k * 1024); } while (0)
; #define PG8_LDB(dst, b, h) do { _Pragma("unroll") for (int n = 0; n < 2; ++n) _Pragma("unroll") for (int k = 0; k < 2; ++k) dst[n][k] = *(const PG8_LAS bf16x8*)(lds + PG8_SB(b, h) + boff + n * 2048 + k * 1024); } while (0)
; #define PG8_MMA(ai, bj, At, Bt) do { __builtin_amdgcn_s_setprio(1); _Pragma("unroll") for (int m = 0; m < 4; ++m) _Pragma("unroll") for (int n = 0; n < 2; ++n) _Pragma("unroll") for (int k = 0; k < 2; ++k) \
;         acc[ai][bj][m][n] = __builtin_amdgcn_mfma_f32_16x16x32_bf16(Bt[n][k], At[m][k], acc[ai][bj][m][n], 0, 0, 0); __builtin_amdgcn_s_setprio(0); } while (0)
; template <class Epi, class Sched, bool ALIGN_EPI = false, bool SP2 = false>
; __device__ __forceinline__ void gemm_phase(PG8_LAS unsigned char* lds, const Gemm g, const Sched& S, const Epi& E) {
;     ...
;             PG8_LDB(B0, 0, 0); PG8_LDB(B1, 0, 1); PG8_SCHED; PG8_LDA(At, 0, 0); PG8_STAGE(PG8_SA(1, 1), a1 + hstep, voffA);
;             PG8_WAIT_V(8); PG8_WAIT_L(0); PG8_BAR; PG8_MMA(0, 0, At, B0); PG8_MMA(0, 1, At, B1); PG8_BAR; PG8_SCHED;
;             PG8_LDA(At, 0, 1); PG8_STAGE(PG8_SB(0, 0), b2, voffB); PG8_STAGE(PG8_SB(0, 1), b2 + hstep, voffB); PG8_STAGE(PG8_SA(0, 0), a2, voffA);
;             PG8_WAIT_V(8); PG8_WAIT_L(0); PG8_BAR; PG8_MMA(1, 0, At, B0); PG8_MMA(1, 1, At, B1); PG8_BAR; PG8_SCHED;
;             PG8_LDB(B0, 1, 0); PG8_LDB(B1, 1, 1); PG8_SCHED; PG8_LDA(At, 1, 0); PG8_STAGE(PG8_SA(0, 1), a2 + hstep, voffA);
;             PG8_WAIT_V(8); PG8_WAIT_L(0); PG8_BAR; PG8_MMA(0, 0, At, B0); PG8_MMA(0, 1, At, B1); PG8_BAR; PG8_SCHED;
;             PG8_LDA(At, 1, 1); PG8_STAGE(PG8_SB(1, 0), b3, voffB); PG8_STAGE(PG8_SB(1, 1), b3 + hstep, voffB); PG8_STAGE(PG8_SA(1, 0), a3, voffA);
;             PG8_WAIT_V(8); PG8_WAIT_L(0); PG8_BAR; PG8_MMA(1, 0, At, B0); PG8_MMA(1, 1, At, B1); PG8_BAR; PG8_SCHED;
;     ...
;         if constexpr (ALIGN_EPI) { if (wr == 0) PG8_BAR; }
	s_add_i32 s76, 0, 0x18000
	s_add_i32 s77, 0, 0x1c000
	v_add_u32_e32 v108, s76, v206
	v_add_u32_e32 v156, s77, v206
	ds_read_b128 v[80:83], v108
	ds_read_b128 v[84:87], v108 offset:1024
	ds_read_b128 v[104:107], v108 offset:2048
	ds_read_b128 v[108:111], v108 offset:3072
	ds_read_b128 v[128:131], v156
	ds_read_b128 v[136:139], v156 offset:1024
	ds_read_b128 v[152:155], v156 offset:2048
	ds_read_b128 v[156:159], v156 offset:3072
	s_add_u32 s64, s64, 0x4000
	s_addc_u32 s65, s65, 0
	s_mov_b32 m0, s50
	ds_read_b128 v[160:163], v207 offset:32768
	ds_read_b128 v[164:167], v207 offset:33792
	ds_read_b128 v[168:171], v207 offset:34816
	ds_read_b128 v[172:175], v207 offset:35840
	ds_read_b128 v[176:179], v207 offset:36864
	ds_read_b128 v[180:183], v207 offset:37888
	ds_read_b128 v[198:201], v207 offset:38912
	ds_read_b128 v[202:205], v207 offset:39936
	global_load_lds_dwordx4 v184, s[64:65]
	s_mov_b32 m0, s51
	s_nop 0
	global_load_lds_dwordx4 v188, s[64:65]
	s_waitcnt vmcnt(8) lgkmcnt(0)
	s_barrier
	v_mfma_f32_16x16x32_bf16 v[148:151], v[80:83], v[160:163], v[148:151]
	v_mfma_f32_16x16x32_bf16 v[144:147], v[104:107], v[160:163], v[144:147]
	v_mfma_f32_16x16x32_bf16 v[124:127], v[80:83], v[168:171], v[124:127]
	v_mfma_f32_16x16x32_bf16 v[120:123], v[104:107], v[168:171], v[120:123]
	v_mfma_f32_16x16x32_bf16 v[100:103], v[80:83], v[176:179], v[100:103]
	v_mfma_f32_16x16x32_bf16 v[96:99], v[104:107], v[176:179], v[96:99]
	v_mfma_f32_16x16x32_bf16 v[76:79], v[80:83], v[198:201], v[76:79]
	v_mfma_f32_16x16x32_bf16 v[72:75], v[104:107], v[198:201], v[72:75]
	v_mfma_f32_16x16x32_bf16 v[148:151], v[84:87], v[164:167], v[148:151]
	v_mfma_f32_16x16x32_bf16 v[144:147], v[108:111], v[164:167], v[144:147]
	v_mfma_f32_16x16x32_bf16 v[124:127], v[84:87], v[172:175], v[124:127]
	v_mfma_f32_16x16x32_bf16 v[120:123], v[108:111], v[172:175], v[120:123]
	v_mfma_f32_16x16x32_bf16 v[100:103], v[84:87], v[180:183], v[100:103]
	v_mfma_f32_16x16x32_bf16 v[96:99], v[108:111], v[180:183], v[96:99]
	v_mfma_f32_16x16x32_bf16 v[76:79], v[84:87], v[202:205], v[76:79]
	v_mfma_f32_16x16x32_bf16 v[72:75], v[108:111], v[202:205], v[72:75]
	v_mfma_f32_16x16x32_bf16 v[140:143], v[128:131], v[160:163], v[140:143]
	v_mfma_f32_16x16x32_bf16 v[132:135], v[152:155], v[160:163], v[132:135]
	v_mfma_f32_16x16x32_bf16 v[116:119], v[128:131], v[168:171], v[116:119]
	v_mfma_f32_16x16x32_bf16 v[112:115], v[152:155], v[168:171], v[112:115]
	v_mfma_f32_16x16x32_bf16 v[92:95], v[128:131], v[176:179], v[92:95]
	v_mfma_f32_16x16x32_bf16 v[88:91], v[152:155], v[176:179], v[88:91]
	v_mfma_f32_16x16x32_bf16 v[68:71], v[128:131], v[198:201], v[68:71]
	v_mfma_f32_16x16x32_bf16 v[64:67], v[152:155], v[198:201], v[64:67]
	v_mfma_f32_16x16x32_bf16 v[140:143], v[136:139], v[164:167], v[140:143]
	v_mfma_f32_16x16x32_bf16 v[132:135], v[156:159], v[164:167], v[132:135]
	v_mfma_f32_16x16x32_bf16 v[116:119], v[136:139], v[172:175], v[116:119]
	v_mfma_f32_16x16x32_bf16 v[112:115], v[156:159], v[172:175], v[112:115]
	v_mfma_f32_16x16x32_bf16 v[92:95], v[136:139], v[180:183], v[92:95]
	v_mfma_f32_16x16x32_bf16 v[88:91], v[156:159], v[180:183], v[88:91]
	v_mfma_f32_16x16x32_bf16 v[68:71], v[136:139], v[202:205], v[68:71]
	v_mfma_f32_16x16x32_bf16 v[64:67], v[156:159], v[202:205], v[64:67]
	s_barrier
	s_add_u32 s64, s20, 0x8000
	s_addc_u32 s65, s21, 0
	s_add_i32 s76, s76, s39
	s_mov_b32 m0, s76
	ds_read_b128 v[160:163], v207 offset:49152
	ds_read_b128 v[164:167], v207 offset:50176
	ds_read_b128 v[168:171], v207 offset:51200
	ds_read_b128 v[172:175], v207 offset:52224
	ds_read_b128 v[176:179], v207 offset:53248
	ds_read_b128 v[180:183], v207 offset:54272
	ds_read_b128 v[198:201], v207 offset:55296
	ds_read_b128 v[202:205], v207 offset:56320
	global_load_lds_dwordx4 v186, s[64:65]
	s_add_i32 m0, s76, 0x2000
	s_add_u32 s20, s20, 0xc000
	v_lshl_add_u64 v[208:209], s[64:65], 0, v[190:191]
	s_addc_u32 s21, s21, 0
	s_add_i32 s64, s77, s39
	global_load_lds_dwordx4 v[208:209], off
	s_mov_b32 m0, s64
	s_nop 0
	global_load_lds_dwordx4 v186, s[20:21]
	s_add_i32 m0, s64, 0x2000
	s_nop 0
	global_load_lds_dwordx4 v190, s[20:21]
	s_mov_b32 m0, s56
	s_nop 0
	global_load_lds_dwordx4 v184, s[18:19]
	s_mov_b32 m0, s57
	s_nop 0
	global_load_lds_dwordx4 v188, s[18:19]
	s_waitcnt vmcnt(8) lgkmcnt(0)
	s_barrier
	v_mfma_f32_16x16x32_bf16 v[60:63], v[80:83], v[160:163], v[60:63]
	v_mfma_f32_16x16x32_bf16 v[56:59], v[104:107], v[160:163], v[56:59]
	v_mfma_f32_16x16x32_bf16 v[44:47], v[80:83], v[168:171], v[44:47]
	v_mfma_f32_16x16x32_bf16 v[40:43], v[104:107], v[168:171], v[40:43]
	v_mfma_f32_16x16x32_bf16 v[28:31], v[80:83], v[176:179], v[28:31]
	v_mfma_f32_16x16x32_bf16 v[24:27], v[104:107], v[176:179], v[24:27]
	v_mfma_f32_16x16x32_bf16 v[12:15], v[80:83], v[198:201], v[12:15]
	v_mfma_f32_16x16x32_bf16 v[8:11], v[104:107], v[198:201], v[8:11]
	v_mfma_f32_16x16x32_bf16 v[60:63], v[84:87], v[164:167], v[60:63]
	v_mfma_f32_16x16x32_bf16 v[56:59], v[108:111], v[164:167], v[56:59]
	v_mfma_f32_16x16x32_bf16 v[44:47], v[84:87], v[172:175], v[44:47]
	v_mfma_f32_16x16x32_bf16 v[40:43], v[108:111], v[172:175], v[40:43]
	v_mfma_f32_16x16x32_bf16 v[28:31], v[84:87], v[180:183], v[28:31]
	v_mfma_f32_16x16x32_bf16 v[24:27], v[108:111], v[180:183], v[24:27]
	v_mfma_f32_16x16x32_bf16 v[12:15], v[84:87], v[202:205], v[12:15]
	v_mfma_f32_16x16x32_bf16 v[8:11], v[108:111], v[202:205], v[8:11]
	v_mfma_f32_16x16x32_bf16 v[52:55], v[128:131], v[160:163], v[52:55]
	v_mfma_f32_16x16x32_bf16 v[48:51], v[152:155], v[160:163], v[48:51]
	v_mfma_f32_16x16x32_bf16 v[36:39], v[128:131], v[168:171], v[36:39]
	v_mfma_f32_16x16x32_bf16 v[32:35], v[152:155], v[168:171], v[32:35]
	v_mfma_f32_16x16x32_bf16 v[20:23], v[128:131], v[176:179], v[20:23]
	v_mfma_f32_16x16x32_bf16 v[16:19], v[152:155], v[176:179], v[16:19]
	v_mfma_f32_16x16x32_bf16 v[4:7], v[128:131], v[198:201], v[4:7]
	v_mfma_f32_16x16x32_bf16 v[0:3], v[152:155], v[198:201], v[0:3]
	v_mfma_f32_16x16x32_bf16 v[52:55], v[136:139], v[164:167], v[52:55]
	v_mfma_f32_16x16x32_bf16 v[48:51], v[156:159], v[164:167], v[48:51]
	v_mfma_f32_16x16x32_bf16 v[36:39], v[136:139], v[172:175], v[36:39]
	v_mfma_f32_16x16x32_bf16 v[32:35], v[156:159], v[172:175], v[32:35]
	v_mfma_f32_16x16x32_bf16 v[20:23], v[136:139], v[180:183], v[20:23]
	v_mfma_f32_16x16x32_bf16 v[16:19], v[156:159], v[180:183], v[16:19]
	v_mfma_f32_16x16x32_bf16 v[4:7], v[136:139], v[202:205], v[4:7]
	v_mfma_f32_16x16x32_bf16 v[0:3], v[156:159], v[202:205], v[0:3]
	s_barrier
	s_add_u32 s16, s16, 0x10000
	s_addc_u32 s17, s17, 0
	s_add_u32 s66, s66, 0x10000
	s_addc_u32 s67, s67, 0
	s_cmp_ge_u32 s75, s53
	s_mov_b32 s18, s75
	s_cbranch_scc0 .LBB0_1322
	s_and_b64 vcc, exec, s[12:13]
	s_cbranch_vccz .LBB0_1325
	s_barrier

; #define PG8_STAGE(bufoff, gbase, voff) do { _Pragma("unroll") for (int _i = 0; _i < 2; ++_i) \
;         __builtin_amdgcn_global_load_lds((const unsigned*)((const char*)(gbase) + (voff)[_i]), (PG8_LAS unsigned*)(lds + (bufoff) + ldsw + _i * 8192), 16, 0, 0); } while (0)
; #define PG8_LDA(dst, b, h) do { _Pragma("unroll") for (int m = 0; m < 4; ++m) _Pragma("unroll") for (int k = 0; k < 2; ++k) dst[m][k] = *(const PG8_LAS bf16x8*)(lds + PG8_SA(b, h) + aoff + m * 2048 + k * 1024); } while (0)
; #define PG8_LDB(dst, b, h) do { _Pragma("unroll") for (int n = 0; n < 2; ++n) _Pragma("unroll") for (int k = 0; k < 2; ++k) dst[n][k] = *(const PG8_LAS bf16x8*)(lds + PG8_SB(b, h) + boff + n * 2048 + k * 1024); } while (0)
; template <class Epi, class Sched, bool ALIGN_EPI = false, bool SP2 = false>
; __device__ __forceinline__ void gemm_phase(PG8_LAS unsigned char* lds, const Gemm g, const Sched& S, const Epi& E) {
;     ...
;         for (int t = 0; t < nt; t += 2) {
;             const bool last = (t == nt - 2);
;             const char* a1 = cA + (size_t)(t + 1) * kstep;
;             const char* a2 = last ? nA : cA + (size_t)(t + 2) * kstep; const char* b2 = last ? nB : cB + (size_t)(t + 2) * kstep;
;             const char* a3 = a2 + kstep; const char* b3 = b2 + kstep;
;             if (last && has_next) S.a_ready(nxt);
;             if constexpr (SP2) {
;             PG8_LDB(B0, 0, 0); PG8_LDB(B1, 0, 1); PG8_SCHED; PG8_LDA(At, 0, 0); PG8_STAGE(PG8_SA(1, 1), a1 + hstep, voffA);
;             PG8_WAIT_V(8); PG8_WAIT_L(0); PG8_BAR; PG8_MMA(0, 0, At, B0); PG8_MMA(0, 1, At, B1); PG8_BAR; PG8_SCHED;
;             PG8_LDA(At, 0, 1); PG8_STAGE(PG8_SB(0, 0), b2, voffB); PG8_STAGE(PG8_SB(0, 1), b2 + hstep, voffB); PG8_STAGE(PG8_SA(0, 0), a2, voffA);
;             PG8_WAIT_V(8); PG8_WAIT_L(0); PG8_BAR; PG8_MMA(1, 0, At, B0); PG8_MMA(1, 1, At, B1); PG8_BAR; PG8_SCHED;
;             PG8_LDB(B0, 1, 0); PG8_LDB(B1, 1, 1); PG8_SCHED; PG8_LDA(At, 1, 0); PG8_STAGE(PG8_SA(0, 1), a2 + hstep, voffA);
;             PG8_WAIT_V(8); PG8_WAIT_L(0); PG8_BAR; PG8_MMA(0, 0, At, B0); PG8_MMA(0, 1, At, B1); PG8_BAR; PG8_SCHED;
;             PG8_LDA(At, 1, 1); PG8_STAGE(PG8_SB(1, 0), b3, voffB); PG8_STAGE(PG8_SB(1, 1), b3 + hstep, voffB); PG8_STAGE(PG8_SA(1, 0), a3, voffA);
;             PG8_WAIT_V(8); PG8_WAIT_L(0); PG8_BAR; PG8_MMA(1, 0, At, B0); PG8_MMA(1, 1, At, B1); PG8_BAR; PG8_SCHED;
.LBB0_1356:
	s_add_u32 s20, s18, 0x4000
	s_addc_u32 s21, s19, 0
	s_cmp_eq_u32 s68, 12
	s_cselect_b32 s64, s40, s20
	s_cselect_b32 s65, s11, s21
	s_cselect_b32 s62, s61, s66
	s_cselect_b32 s63, s9, s67
	s_add_u32 s20, s64, 0x8000
	s_addc_u32 s21, s65, 0
	s_add_i32 s69, 0, 0x10000
	s_add_i32 s72, 0, 0x14000
	v_add_u32_e32 v140, s69, v162
	v_add_u32_e32 v160, s72, v162
	ds_read_b128 v[128:131], v140
	ds_read_b128 v[132:135], v140 offset:1024
	ds_read_b128 v[136:139], v140 offset:2048
	ds_read_b128 v[140:143], v140 offset:3072
	ds_read_b128 v[156:159], v160
	ds_read_b128 v[164:167], v160 offset:1024
	ds_read_b128 v[168:171], v160 offset:2048
	ds_read_b128 v[172:175], v160 offset:3072
	s_add_i32 m0, s37, 0xc000
	ds_read_b128 v[176:179], v163
	ds_read_b128 v[180:183], v163 offset:1024
	ds_read_b128 v[184:187], v163 offset:2048
	ds_read_b128 v[188:191], v163 offset:3072
	ds_read_b128 v[192:195], v163 offset:4096
	ds_read_b128 v[196:199], v163 offset:5120
	ds_read_b128 v[200:203], v163 offset:6144
	ds_read_b128 v[204:207], v163 offset:7168
	global_load_lds_dwordx4 v152, s[18:19]
	s_add_i32 m0, s37, 0xe000
	s_nop 0
	global_load_lds_dwordx4 v154, s[18:19]
	s_waitcnt vmcnt(8) lgkmcnt(0)
	s_barrier
	v_mfma_f32_16x16x32_bf16 v[124:127], v[128:131], v[176:179], v[124:127]
	v_mfma_f32_16x16x32_bf16 v[120:123], v[136:139], v[176:179], v[120:123]
	v_mfma_f32_16x16x32_bf16 v[108:111], v[128:131], v[184:187], v[108:111]
	v_mfma_f32_16x16x32_bf16 v[104:107], v[136:139], v[184:187], v[104:107]
	v_mfma_f32_16x16x32_bf16 v[92:95], v[128:131], v[192:195], v[92:95]
	v_mfma_f32_16x16x32_bf16 v[88:91], v[136:139], v[192:195], v[88:91]
	v_mfma_f32_16x16x32_bf16 v[76:79], v[128:131], v[200:203], v[76:79]
	v_mfma_f32_16x16x32_bf16 v[72:75], v[136:139], v[200:203], v[72:75]
	v_mfma_f32_16x16x32_bf16 v[124:127], v[132:135], v[180:183], v[124:127]
	v_mfma_f32_16x16x32_bf16 v[120:123], v[140:143], v[180:183], v[120:123]
	v_mfma_f32_16x16x32_bf16 v[108:111], v[132:135], v[188:191], v[108:111]
	v_mfma_f32_16x16x32_bf16 v[104:107], v[140:143], v[188:191], v[104:107]
	v_mfma_f32_16x16x32_bf16 v[92:95], v[132:135], v[196:199], v[92:95]
	v_mfma_f32_16x16x32_bf16 v[88:91], v[140:143], v[196:199], v[88:91]
	v_mfma_f32_16x16x32_bf16 v[76:79], v[132:135], v[204:207], v[76:79]
	v_mfma_f32_16x16x32_bf16 v[72:75], v[140:143], v[204:207], v[72:75]
	v_mfma_f32_16x16x32_bf16 v[116:119], v[156:159], v[176:179], v[116:119]
	v_mfma_f32_16x16x32_bf16 v[112:115], v[168:171], v[176:179], v[112:115]
	v_mfma_f32_16x16x32_bf16 v[100:103], v[156:159], v[184:187], v[100:103]
	v_mfma_f32_16x16x32_bf16 v[96:99], v[168:171], v[184:187], v[96:99]
	v_mfma_f32_16x16x32_bf16 v[84:87], v[156:159], v[192:195], v[84:87]
	v_mfma_f32_16x16x32_bf16 v[80:83], v[168:171], v[192:195], v[80:83]
	v_mfma_f32_16x16x32_bf16 v[68:71], v[156:159], v[200:203], v[68:71]
	v_mfma_f32_16x16x32_bf16 v[64:67], v[168:171], v[200:203], v[64:67]
	v_mfma_f32_16x16x32_bf16 v[116:119], v[164:167], v[180:183], v[116:119]
	v_mfma_f32_16x16x32_bf16 v[112:115], v[172:175], v[180:183], v[112:115]
	v_mfma_f32_16x16x32_bf16 v[100:103], v[164:167], v[188:191], v[100:103]
	v_mfma_f32_16x16x32_bf16 v[96:99], v[172:175], v[188:191], v[96:99]
	v_mfma_f32_16x16x32_bf16 v[84:87], v[164:167], v[196:199], v[84:87]
	v_mfma_f32_16x16x32_bf16 v[80:83], v[172:175], v[196:199], v[80:83]
	v_mfma_f32_16x16x32_bf16 v[68:71], v[164:167], v[204:207], v[68:71]
	v_mfma_f32_16x16x32_bf16 v[64:67], v[172:175], v[204:207], v[64:67]
	s_barrier
	s_add_i32 s69, s69, s30
	s_mov_b32 m0, s69
	ds_read_b128 v[176:179], v163 offset:16384
	ds_read_b128 v[180:183], v163 offset:17408
	ds_read_b128 v[184:187], v163 offset:18432
	ds_read_b128 v[188:191], v163 offset:19456
	ds_read_b128 v[192:195], v163 offset:20480
	ds_read_b128 v[196:199], v163 offset:21504
	ds_read_b128 v[200:203], v163 offset:22528
	ds_read_b128 v[204:207], v163 offset:23552
	global_load_lds_dwordx4 v148, s[62:63]
	s_add_i32 m0, s69, 0x2000
	s_add_u32 s70, s62, 0x4000
	s_addc_u32 s71, s63, 0
	s_add_i32 s69, s72, s30
	global_load_lds_dwordx4 v144, s[62:63]
	s_mov_b32 m0, s69
	s_nop 0
	global_load_lds_dwordx4 v148, s[70:71]
	s_add_i32 m0, s69, 0x2000
	s_nop 0
	global_load_lds_dwordx4 v144, s[70:71]
	s_mov_b32 m0, s37
	s_nop 0
	global_load_lds_dwordx4 v150, s[64:65]
	s_mov_b32 m0, s39
	s_nop 0
	global_load_lds_dwordx4 v146, s[64:65]
	s_waitcnt vmcnt(8) lgkmcnt(0)
	s_barrier
	v_mfma_f32_16x16x32_bf16 v[60:63], v[128:131], v[176:179], v[60:63]
	v_mfma_f32_16x16x32_bf16 v[56:59], v[136:139], v[176:179], v[56:59]
	v_mfma_f32_16x16x32_bf16 v[44:47], v[128:131], v[184:187], v[44:47]
	v_mfma_f32_16x16x32_bf16 v[40:43], v[136:139], v[184:187], v[40:43]
	v_mfma_f32_16x16x32_bf16 v[28:31], v[128:131], v[192:195], v[28:31]
	v_mfma_f32_16x16x32_bf16 v[24:27], v[136:139], v[192:195], v[24:27]
	v_mfma_f32_16x16x32_bf16 v[12:15], v[128:131], v[200:203], v[12:15]
	v_mfma_f32_16x16x32_bf16 v[8:11], v[136:139], v[200:203], v[8:11]
	v_mfma_f32_16x16x32_bf16 v[60:63], v[132:135], v[180:183], v[60:63]
	v_mfma_f32_16x16x32_bf16 v[56:59], v[140:143], v[180:183], v[56:59]
	v_mfma_f32_16x16x32_bf16 v[44:47], v[132:135], v[188:191], v[44:47]
	v_mfma_f32_16x16x32_bf16 v[40:43], v[140:143], v[188:191], v[40:43]
	v_mfma_f32_16x16x32_bf16 v[28:31], v[132:135], v[196:199], v[28:31]
	v_mfma_f32_16x16x32_bf16 v[24:27], v[140:143], v[196:199], v[24:27]
	v_mfma_f32_16x16x32_bf16 v[12:15], v[132:135], v[204:207], v[12:15]
	v_mfma_f32_16x16x32_bf16 v[8:11], v[140:143], v[204:207], v[8:11]
	v_mfma_f32_16x16x32_bf16 v[52:55], v[156:159], v[176:179], v[52:55]
	v_mfma_f32_16x16x32_bf16 v[48:51], v[168:171], v[176:179], v[48:51]
	v_mfma_f32_16x16x32_bf16 v[36:39], v[156:159], v[184:187], v[36:39]
	v_mfma_f32_16x16x32_bf16 v[32:35], v[168:171], v[184:187], v[32:35]
	v_mfma_f32_16x16x32_bf16 v[20:23], v[156:159], v[192:195], v[20:23]
	v_mfma_f32_16x16x32_bf16 v[16:19], v[168:171], v[192:195], v[16:19]
	v_mfma_f32_16x16x32_bf16 v[4:7], v[156:159], v[200:203], v[4:7]
	v_mfma_f32_16x16x32_bf16 v[0:3], v[168:171], v[200:203], v[0:3]
	v_mfma_f32_16x16x32_bf16 v[52:55], v[164:167], v[180:183], v[52:55]
	v_mfma_f32_16x16x32_bf16 v[48:51], v[172:175], v[180:183], v[48:51]
	v_mfma_f32_16x16x32_bf16 v[36:39], v[164:167], v[188:191], v[36:39]
	v_mfma_f32_16x16x32_bf16 v[32:35], v[172:175], v[188:191], v[32:35]
	v_mfma_f32_16x16x32_bf16 v[20:23], v[164:167], v[196:199], v[20:23]
	v_mfma_f32_16x16x32_bf16 v[16:19], v[172:175], v[196:199], v[16:19]
	v_mfma_f32_16x16x32_bf16 v[4:7], v[164:167], v[204:207], v[4:7]
	v_mfma_f32_16x16x32_bf16 v[0:3], v[172:175], v[204:207], v[0:3]
	s_barrier
; #define PG8_STAGE(bufoff, gbase, voff) do { _Pragma("unroll") for (int _i = 0; _i < 2; ++_i) \
;         __builtin_amdgcn_global_load_lds((const unsigned*)((const char*)(gbase) + (voff)[_i]), (PG8_LAS unsigned*)(lds + (bufoff) + ldsw + _i * 8192), 16, 0, 0); } while (0)
; #define PG8_LDA(dst, b, h) do { _Pragma("unroll") for (int m = 0; m < 4; ++m) _Pragma("unroll") for (int k = 0; k < 2; ++k) dst[m][k] = *(const PG8_LAS bf16x8*)(lds + PG8_SA(b, h) + aoff + m * 2048 + k * 1024); } while (0)
; #define PG8_LDB(dst, b, h) do { _Pragma("unroll") for (int n = 0; n < 2; ++n) _Pragma("unroll") for (int k = 0; k < 2; ++k) dst[n][k] = *(const PG8_LAS bf16x8*)(lds + PG8_SB(b, h) + boff + n * 2048 + k * 1024); } while (0)
; #define PG8_MMA(ai, bj, At, Bt) do { __builtin_amdgcn_s_setprio(1); _Pragma("unroll") for (int m = 0; m < 4; ++m) _Pragma("unroll") for (int n = 0; n < 2; ++n) _Pragma("unroll") for (int k = 0; k < 2; ++k) \
;         acc[ai][bj][m][n] = __builtin_amdgcn_mfma_f32_16x16x32_bf16(Bt[n][k], At[m][k], acc[ai][bj][m][n], 0, 0, 0); __builtin_amdgcn_s_setprio(0); } while (0)
; template <class Epi, class Sched, bool ALIGN_EPI = false, bool SP2 = false>
; __device__ __forceinline__ void gemm_phase(PG8_LAS unsigned char* lds, const Gemm g, const Sched& S, const Epi& E) {
;     ...
;             PG8_LDB(B0, 0, 0); PG8_LDB(B1, 0, 1); PG8_SCHED; PG8_LDA(At, 0, 0); PG8_STAGE(PG8_SA(1, 1), a1 + hstep, voffA);
;             PG8_WAIT_V(8); PG8_WAIT_L(0); PG8_BAR; PG8_MMA(0, 0, At, B0); PG8_MMA(0, 1, At, B1); PG8_BAR; PG8_SCHED;
;             PG8_LDA(At, 0, 1); PG8_STAGE(PG8_SB(0, 0), b2, voffB); PG8_STAGE(PG8_SB(0, 1), b2 + hstep, voffB); PG8_STAGE(PG8_SA(0, 0), a2, voffA);
;             PG8_WAIT_V(8); PG8_WAIT_L(0); PG8_BAR; PG8_MMA(1, 0, At, B0); PG8_MMA(1, 1, At, B1); PG8_BAR; PG8_SCHED;
;             PG8_LDB(B0, 1, 0); PG8_LDB(B1, 1, 1); PG8_SCHED; PG8_LDA(At, 1, 0); PG8_STAGE(PG8_SA(0, 1), a2 + hstep, voffA);
;             PG8_WAIT_V(8); PG8_WAIT_L(0); PG8_BAR; PG8_MMA(0, 0, At, B0); PG8_MMA(0, 1, At, B1); PG8_BAR; PG8_SCHED;
;             PG8_LDA(At, 1, 1); PG8_STAGE(PG8_SB(1, 0), b3, voffB); PG8_STAGE(PG8_SB(1, 1), b3 + hstep, voffB); PG8_STAGE(PG8_SA(1, 0), a3, voffA);
;             PG8_WAIT_V(8); PG8_WAIT_L(0); PG8_BAR; PG8_MMA(1, 0, At, B0); PG8_MMA(1, 1, At, B1); PG8_BAR; PG8_SCHED;
;     ...
;         if constexpr (ALIGN_EPI) { if (wr == 0) PG8_BAR; }
	s_add_i32 s69, 0, 0x18000
	s_add_i32 s70, 0, 0x1c000
	v_add_u32_e32 v140, s69, v162
	v_add_u32_e32 v160, s70, v162
	ds_read_b128 v[128:131], v140
	ds_read_b128 v[132:135], v140 offset:1024
	ds_read_b128 v[136:139], v140 offset:2048
	ds_read_b128 v[140:143], v140 offset:3072
	ds_read_b128 v[156:159], v160
	ds_read_b128 v[164:167], v160 offset:1024
	ds_read_b128 v[168:171], v160 offset:2048
	ds_read_b128 v[172:175], v160 offset:3072
	s_add_u32 s64, s64, 0x4000
	s_addc_u32 s65, s65, 0
	s_mov_b32 m0, s41
	ds_read_b128 v[176:179], v163 offset:32768
	ds_read_b128 v[180:183], v163 offset:33792
	ds_read_b128 v[184:187], v163 offset:34816
	ds_read_b128 v[188:191], v163 offset:35840
	ds_read_b128 v[192:195], v163 offset:36864
	ds_read_b128 v[196:199], v163 offset:37888
	ds_read_b128 v[200:203], v163 offset:38912
	ds_read_b128 v[204:207], v163 offset:39936
	global_load_lds_dwordx4 v150, s[64:65]
	s_mov_b32 m0, s42
	s_nop 0
	global_load_lds_dwordx4 v146, s[64:65]
	s_waitcnt vmcnt(8) lgkmcnt(0)
	s_barrier
	v_mfma_f32_16x16x32_bf16 v[124:127], v[128:131], v[176:179], v[124:127]
	v_mfma_f32_16x16x32_bf16 v[120:123], v[136:139], v[176:179], v[120:123]
	v_mfma_f32_16x16x32_bf16 v[108:111], v[128:131], v[184:187], v[108:111]
	v_mfma_f32_16x16x32_bf16 v[104:107], v[136:139], v[184:187], v[104:107]
	v_mfma_f32_16x16x32_bf16 v[92:95], v[128:131], v[192:195], v[92:95]
	v_mfma_f32_16x16x32_bf16 v[88:91], v[136:139], v[192:195], v[88:91]
	v_mfma_f32_16x16x32_bf16 v[76:79], v[128:131], v[200:203], v[76:79]
	v_mfma_f32_16x16x32_bf16 v[72:75], v[136:139], v[200:203], v[72:75]
	v_mfma_f32_16x16x32_bf16 v[124:127], v[132:135], v[180:183], v[124:127]
	v_mfma_f32_16x16x32_bf16 v[120:123], v[140:143], v[180:183], v[120:123]
	v_mfma_f32_16x16x32_bf16 v[108:111], v[132:135], v[188:191], v[108:111]
	v_mfma_f32_16x16x32_bf16 v[104:107], v[140:143], v[188:191], v[104:107]
	v_mfma_f32_16x16x32_bf16 v[92:95], v[132:135], v[196:199], v[92:95]
	v_mfma_f32_16x16x32_bf16 v[88:91], v[140:143], v[196:199], v[88:91]
	v_mfma_f32_16x16x32_bf16 v[76:79], v[132:135], v[204:207], v[76:79]
	v_mfma_f32_16x16x32_bf16 v[72:75], v[140:143], v[204:207], v[72:75]
	v_mfma_f32_16x16x32_bf16 v[116:119], v[156:159], v[176:179], v[116:119]
	v_mfma_f32_16x16x32_bf16 v[112:115], v[168:171], v[176:179], v[112:115]
	v_mfma_f32_16x16x32_bf16 v[100:103], v[156:159], v[184:187], v[100:103]
	v_mfma_f32_16x16x32_bf16 v[96:99], v[168:171], v[184:187], v[96:99]
	v_mfma_f32_16x16x32_bf16 v[84:87], v[156:159], v[192:195], v[84:87]
	v_mfma_f32_16x16x32_bf16 v[80:83], v[168:171], v[192:195], v[80:83]
	v_mfma_f32_16x16x32_bf16 v[68:71], v[156:159], v[200:203], v[68:71]
	v_mfma_f32_16x16x32_bf16 v[64:67], v[168:171], v[200:203], v[64:67]
	v_mfma_f32_16x16x32_bf16 v[116:119], v[164:167], v[180:183], v[116:119]
	v_mfma_f32_16x16x32_bf16 v[112:115], v[172:175], v[180:183], v[112:115]
	v_mfma_f32_16x16x32_bf16 v[100:103], v[164:167], v[188:191], v[100:103]
	v_mfma_f32_16x16x32_bf16 v[96:99], v[172:175], v[188:191], v[96:99]
	v_mfma_f32_16x16x32_bf16 v[84:87], v[164:167], v[196:199], v[84:87]
	v_mfma_f32_16x16x32_bf16 v[80:83], v[172:175], v[196:199], v[80:83]
	v_mfma_f32_16x16x32_bf16 v[68:71], v[164:167], v[204:207], v[68:71]
	v_mfma_f32_16x16x32_bf16 v[64:67], v[172:175], v[204:207], v[64:67]
	s_barrier
	s_add_u32 s64, s62, 0x8000
	s_addc_u32 s65, s63, 0
	s_add_i32 s69, s69, s30
	s_mov_b32 m0, s69
	ds_read_b128 v[176:179], v163 offset:49152
	ds_read_b128 v[180:183], v163 offset:50176
	ds_read_b128 v[184:187], v163 offset:51200
	ds_read_b128 v[188:191], v163 offset:52224
	ds_read_b128 v[192:195], v163 offset:53248
	ds_read_b128 v[196:199], v163 offset:54272
	ds_read_b128 v[200:203], v163 offset:55296
	ds_read_b128 v[204:207], v163 offset:56320
	global_load_lds_dwordx4 v148, s[64:65]
	s_add_i32 m0, s69, 0x2000
	s_add_u32 s62, s62, 0xc000
	v_lshl_add_u64 v[160:161], s[64:65], 0, v[144:145]
	s_addc_u32 s63, s63, 0
	s_add_i32 s64, s70, s30
	global_load_lds_dwordx4 v[160:161], off
	s_mov_b32 m0, s64
	s_nop 0
	global_load_lds_dwordx4 v148, s[62:63]
	s_add_i32 m0, s64, 0x2000
	s_nop 0
	global_load_lds_dwordx4 v144, s[62:63]
	s_mov_b32 m0, s54
	s_nop 0
	global_load_lds_dwordx4 v150, s[20:21]
	s_mov_b32 m0, s55
	s_nop 0
	global_load_lds_dwordx4 v146, s[20:21]
	s_waitcnt vmcnt(8) lgkmcnt(0)
	s_barrier
	v_mfma_f32_16x16x32_bf16 v[60:63], v[128:131], v[176:179], v[60:63]
	v_mfma_f32_16x16x32_bf16 v[56:59], v[136:139], v[176:179], v[56:59]
	v_mfma_f32_16x16x32_bf16 v[44:47], v[128:131], v[184:187], v[44:47]
	v_mfma_f32_16x16x32_bf16 v[40:43], v[136:139], v[184:187], v[40:43]
	v_mfma_f32_16x16x32_bf16 v[28:31], v[128:131], v[192:195], v[28:31]
	v_mfma_f32_16x16x32_bf16 v[24:27], v[136:139], v[192:195], v[24:27]
	v_mfma_f32_16x16x32_bf16 v[12:15], v[128:131], v[200:203], v[12:15]
	v_mfma_f32_16x16x32_bf16 v[8:11], v[136:139], v[200:203], v[8:11]
	v_mfma_f32_16x16x32_bf16 v[60:63], v[132:135], v[180:183], v[60:63]
	v_mfma_f32_16x16x32_bf16 v[56:59], v[140:143], v[180:183], v[56:59]
	v_mfma_f32_16x16x32_bf16 v[44:47], v[132:135], v[188:191], v[44:47]
	v_mfma_f32_16x16x32_bf16 v[40:43], v[140:143], v[188:191], v[40:43]
	v_mfma_f32_16x16x32_bf16 v[28:31], v[132:135], v[196:199], v[28:31]
	v_mfma_f32_16x16x32_bf16 v[24:27], v[140:143], v[196:199], v[24:27]
	v_mfma_f32_16x16x32_bf16 v[12:15], v[132:135], v[204:207], v[12:15]
	v_mfma_f32_16x16x32_bf16 v[8:11], v[140:143], v[204:207], v[8:11]
	v_mfma_f32_16x16x32_bf16 v[52:55], v[156:159], v[176:179], v[52:55]
	v_mfma_f32_16x16x32_bf16 v[48:51], v[168:171], v[176:179], v[48:51]
	v_mfma_f32_16x16x32_bf16 v[36:39], v[156:159], v[184:187], v[36:39]
	v_mfma_f32_16x16x32_bf16 v[32:35], v[168:171], v[184:187], v[32:35]
	v_mfma_f32_16x16x32_bf16 v[20:23], v[156:159], v[192:195], v[20:23]
	v_mfma_f32_16x16x32_bf16 v[16:19], v[168:171], v[192:195], v[16:19]
	v_mfma_f32_16x16x32_bf16 v[4:7], v[156:159], v[200:203], v[4:7]
	v_mfma_f32_16x16x32_bf16 v[0:3], v[168:171], v[200:203], v[0:3]
	v_mfma_f32_16x16x32_bf16 v[52:55], v[164:167], v[180:183], v[52:55]
	v_mfma_f32_16x16x32_bf16 v[48:51], v[172:175], v[180:183], v[48:51]
	v_mfma_f32_16x16x32_bf16 v[36:39], v[164:167], v[188:191], v[36:39]
	v_mfma_f32_16x16x32_bf16 v[32:35], v[172:175], v[188:191], v[32:35]
	v_mfma_f32_16x16x32_bf16 v[20:23], v[164:167], v[196:199], v[20:23]
	v_mfma_f32_16x16x32_bf16 v[16:19], v[172:175], v[196:199], v[16:19]
	v_mfma_f32_16x16x32_bf16 v[4:7], v[164:167], v[204:207], v[4:7]
	v_mfma_f32_16x16x32_bf16 v[0:3], v[172:175], v[204:207], v[0:3]
	s_barrier
	s_add_i32 s68, s68, 2
	s_add_u32 s18, s18, 0x10000
	s_addc_u32 s19, s19, 0
	s_add_u32 s66, s66, 0x10000
	s_addc_u32 s67, s67, 0
	s_cmp_gt_u32 s68, 13
	s_cbranch_scc0 .LBB0_1356
	s_and_b64 vcc, exec, s[6:7]
	s_cbranch_vccz .LBB0_1359
	s_barrier
